# attention loop unrolled x4 with fully static LDS ring addressing (V ring of 4 in the former Q staging area, no extra static LDS), running DMA pointers instead of per-tile address recomputation, halved
# speedup vs baseline: 1.0714x; 1.0166x over previous
; DI void phase_attn(int wid0, const Params& p, int L, unsigned char* lds, bool dry) {
;     ...
;         const int qrow0 = meta ? MREG : b * 4096 + 128 * qb, qpos0 = meta ? 0 : 16 + 128 * qb, ntiles = meta ? 1 : 1 + 4 * (qb + 1);
;         if (tid < 130) tab[tid] = (tid < 129) ? biasT[hh * 129 + tid] : -__builtin_inff();
;         int myrow = qrow0 + 32 * rg + r32; if (meta && myrow > MREG + 63) myrow = MREG + 63;
;         const bf16_t* qp = qbuf + (size_t)myrow * 2048 + hh * 256 + psub * 128 + hi * 8;
;         unsigned char* qlds = lds + wid * 8192 + lane * 16;
; #pragma unroll
;         for (int d0 = 0; d0 < 8; ++d0) *(bf16x8*)(qlds + d0 * 1024) = *(const bf16x8*)(qp + d0 * 16);
;         const int wq0 = qpos0 + 32 * rg, qpos = wq0 + r32;
;         const float bfar = biasT[hh * 129 + 128];
;         const bf16_t* kh_ = kbuf + hh * 256; const bf16_t* vh_ = vbuf + hh * 256;
;         attn_stage(kh_ + (size_t)MREG * 2048, vh_ + (size_t)MREG * 2048, koff, voff, ldsl + 65536, wid);
;         f32x16 o[8];
; #pragma unroll
;         for (int d = 0; d < 8; ++d)
; #pragma unroll
;             for (int r = 0; r < 16; ++r) o[d][r] = 0.f;
;         float m_reg = -1e30f, l_reg = 0.f;
.LBB0_97:
	s_or_b64 exec, exec, s[10:11]
	s_lshl_b32 s40, s73, 12
	s_lshl_b32 s10, s75, 7
	s_add_i32 s9, s40, s10
	s_and_b64 s[6:7], s[76:77], exec
	s_cselect_b32 s71, 0x8000, s9
	s_lshl_b32 s6, s75, 2
	s_add_i32 s9, s6, 5
	s_and_b64 s[6:7], s[76:77], exec
	v_ashrrev_i32_e32 v0, 4, v4
	v_readlane_b32 s7, v245, 61
	v_and_b32_e32 v2, 15, v4
	v_lshrrev_b32_e32 v3, 1, v4
	v_add_u32_e32 v0, s7, v0
	v_bitop3_b32 v2, v0, v2, 15 bitop3:0x6c
	v_lshlrev_b32_e32 v0, 12, v0
	v_lshl_or_b32 v0, v2, 4, v0
	v_lshrrev_b32_e32 v2, 2, v4
	v_and_b32_e32 v3, 8, v3
	v_readlane_b32 s7, v245, 63
	v_and_or_b32 v2, v2, 3, v3
	v_lshlrev_b32_e32 v8, 3, v4
	v_add_u32_e32 v3, s7, v4
	v_readlane_b32 s7, v244, 1
	v_and_b32_e32 v7, 31, v4
	v_and_b32_e32 v3, 0xe0, v3
	v_and_b32_e32 v5, 24, v8
	v_lshl_add_u32 v2, v2, 11, s7
	v_or3_b32 v2, v2, v3, v5
	v_or_b32_e32 v3, s41, v7
	v_or_b32_e32 v3, s71, v3
	v_min_i32_e32 v9, 0x803f, v3
	v_cndmask_b32_e64 v10, v3, v9, s[76:77]
	s_cselect_b32 s6, 1, s9
	v_ashrrev_i32_e32 v11, 31, v10
	s_lshl_b32 s12, s49, 8
	v_lshlrev_b64 v[10:11], 12, v[10:11]
	s_ashr_i32 s13, s12, 31
	v_ashrrev_i32_e32 v6, 5, v4
	v_lshl_add_u64 v[10:11], s[0:1], 0, v[10:11]
	s_lshl_b64 s[78:79], s[12:13], 1
	v_readlane_b32 s12, v244, 5
	v_lshl_add_u64 v[10:11], v[10:11], 0, s[78:79]
	v_readlane_b32 s13, v244, 6
	v_lshlrev_b32_e32 v12, 3, v6
	v_ashrrev_i32_e32 v13, 31, v12
	v_lshl_add_u64 v[10:11], s[12:13], 1, v[10:11]
	v_lshl_add_u64 v[14:15], v[12:13], 1, v[10:11]
	global_load_dwordx4 v[248:251], v[14:15], off
	s_ashr_i32 s9, s8, 31
	s_lshl_b64 s[8:9], s[8:9], 2
	v_readlane_b32 s12, v245, 40
	v_lshlrev_b32_e32 v9, 4, v4
	v_readlane_b32 s7, v244, 7
	v_readlane_b32 s13, v245, 41
	s_add_u32 s8, s12, s8
	s_addc_u32 s9, s13, s9
	global_load_dword v176, v1, s[8:9] offset:512
	s_add_u32 s12, s28, s78
	s_addc_u32 s13, s29, s79
	s_mov_b64 s[84:85], s[12:13]
	v_readlane_b32 s8, v245, 38
	v_readlane_b32 s9, v245, 39
	s_add_u32 s8, s8, s78
	v_readlane_b32 s7, v244, 9
	s_addc_u32 s9, s9, s79
	s_mov_b64 s[86:87], s[8:9]
	v_lshl_add_u64 v[178:179], s[12:13], 0, v[0:1]
	v_mov_b32_e32 v131, v0
	s_mov_b64 s[14:15], 0x8000000
	s_add_i32 s7, s7, 0
	v_lshlrev_b32_e32 v2, 1, v2
	s_add_i32 m0, s7, 0x10000
	s_mov_b64 s[12:13], 0x8000100
	v_mov_b32_e32 v3, v1
	v_lshl_add_u64 v[180:181], s[8:9], 0, v[2:3]
	v_mov_b32_e32 v208, v2
	v_lshl_add_u64 v[2:3], v[180:181], 0, s[14:15]
	s_mov_b64 s[8:9], 0x8010000
	global_load_dwordx4 v[252:255], v[14:15], off offset:32
	global_load_dwordx4 v[200:203], v[14:15], off offset:64
	global_load_dwordx4 v[204:207], v[14:15], off offset:96
	global_load_dwordx4 v[164:167], v[14:15], off offset:128
	global_load_dwordx4 v[168:171], v[14:15], off offset:160
	global_load_dwordx4 v[172:175], v[14:15], off offset:192
	global_load_dwordx4 v[232:235], v[14:15], off offset:224
	v_lshl_add_u64 v[10:11], v[178:179], 0, s[14:15]
	global_load_lds_dwordx4 v[10:11], off
	v_lshl_add_u64 v[10:11], v[178:179], 0, s[12:13]
	s_add_i32 m0, s7, 0x12000
	s_nop 0
	global_load_lds_dwordx4 v[10:11], off
	s_add_i32 m0, s7, 0x0
	s_nop 0
	global_load_lds_dwordx4 v[2:3], off
	v_lshl_add_u64 v[2:3], v[180:181], 0, s[8:9]
	s_add_i32 m0, s7, 0x2000
	s_mov_b32 s7, 0
	global_load_lds_dwordx4 v[2:3], off
	s_cmp_lt_i32 s6, 1
	s_cbranch_scc1 .LBB0_114
	s_or_b32 s10, s10, 16
	v_lshlrev_b32_e32 v0, 8, v7
	v_bitop3_b32 v2, v6, v4, 1 bitop3:0x78
	s_and_b64 s[8:9], s[76:77], exec
	v_lshl_add_u32 v193, v2, 4, v0
	v_lshlrev_b32_e32 v2, 1, v4
	s_cselect_b32 s39, 0, s10
	v_and_b32_e32 v0, 0xc0, v9
	v_and_b32_e32 v2, 32, v2
	v_readlane_b32 s48, v244, 17
	s_or_b32 s8, s39, s41
	v_and_b32_e32 v3, 0x100, v8
	v_add3_u32 v0, s48, v0, v2
	v_mov_b32_e32 v14, v1
	v_mov_b32_e32 v15, v1
	s_add_i32 s38, s8, 31
	v_and_b32_e32 v192, 0xe0, v9
	v_lshlrev_b32_e32 v194, 2, v6
	v_add_u32_e32 v195, s8, v7
	v_cmp_gt_u32_e64 s[8:9], 32, v4
	v_lshl_add_u32 v196, v7, 2, s2
	v_lshlrev_b32_e32 v16, 4, v6
	v_cmp_gt_i32_e64 s[10:11], 4, v6
	v_cmp_gt_i32_e64 s[18:19], 2, v6
	v_cmp_gt_i32_e64 s[20:21], 0, v6
	v_cmp_gt_i32_e64 s[22:23], -2, v6
	v_add3_u32 v212, v0, v3, v5
	v_add_u32_e32 v212, 0xffff0000, v212
	v_mov_b32_e32 v0, v1
	v_mov_b32_e32 v2, v1
	v_mov_b32_e32 v3, v1
	v_mov_b32_e32 v4, v1
	v_mov_b32_e32 v5, v1
	v_mov_b32_e32 v6, v1
	v_mov_b32_e32 v7, v1
	v_mov_b32_e32 v8, v1
	v_mov_b32_e32 v9, v1
	v_mov_b32_e32 v10, v1
	v_mov_b32_e32 v11, v1
	v_mov_b32_e32 v12, v1
	v_mov_b32_e32 v13, v1
	v_mov_b64_e32 v[128:129], v[14:15]
	v_mov_b64_e32 v[112:113], v[14:15]
	v_mov_b64_e32 v[96:97], v[14:15]
	v_mov_b64_e32 v[80:81], v[14:15]
	v_mov_b64_e32 v[64:65], v[14:15]
	v_mov_b64_e32 v[48:49], v[14:15]
	v_mov_b64_e32 v[32:33], v[14:15]
	v_or_b32_e32 v197, 1, v194
	v_or_b32_e32 v198, 2, v194
	v_or_b32_e32 v199, 3, v194
	v_readlane_b32 s48, v244, 19
	v_add_u32_e32 v214, s2, v16
	v_mov_b64_e32 v[126:127], v[12:13]
	v_mov_b64_e32 v[124:125], v[10:11]
	v_mov_b64_e32 v[122:123], v[8:9]
	v_mov_b64_e32 v[120:121], v[6:7]
	v_mov_b64_e32 v[118:119], v[4:5]
	v_mov_b64_e32 v[116:117], v[2:3]
	v_mov_b64_e32 v[114:115], v[0:1]
	v_mov_b64_e32 v[110:111], v[12:13]
	v_mov_b64_e32 v[108:109], v[10:11]
	v_mov_b64_e32 v[106:107], v[8:9]
	v_mov_b64_e32 v[104:105], v[6:7]
	v_mov_b64_e32 v[102:103], v[4:5]
	v_mov_b64_e32 v[100:101], v[2:3]
	v_mov_b64_e32 v[98:99], v[0:1]
	v_mov_b64_e32 v[94:95], v[12:13]
	v_mov_b64_e32 v[92:93], v[10:11]
	v_mov_b64_e32 v[90:91], v[8:9]
	v_mov_b64_e32 v[88:89], v[6:7]
	v_mov_b64_e32 v[86:87], v[4:5]
	v_mov_b64_e32 v[84:85], v[2:3]
	v_mov_b64_e32 v[82:83], v[0:1]
	v_mov_b64_e32 v[78:79], v[12:13]
	v_mov_b64_e32 v[76:77], v[10:11]
	v_mov_b64_e32 v[74:75], v[8:9]
	v_mov_b64_e32 v[72:73], v[6:7]
	v_mov_b64_e32 v[70:71], v[4:5]
	v_mov_b64_e32 v[68:69], v[2:3]
	v_mov_b64_e32 v[66:67], v[0:1]
	v_mov_b64_e32 v[62:63], v[12:13]
	v_mov_b64_e32 v[60:61], v[10:11]
	v_mov_b64_e32 v[58:59], v[8:9]
	v_mov_b64_e32 v[56:57], v[6:7]
	v_mov_b64_e32 v[54:55], v[4:5]
	v_mov_b64_e32 v[52:53], v[2:3]
	v_mov_b64_e32 v[50:51], v[0:1]
	v_mov_b64_e32 v[46:47], v[12:13]
	v_mov_b64_e32 v[44:45], v[10:11]
	v_mov_b64_e32 v[42:43], v[8:9]
	v_mov_b64_e32 v[40:41], v[6:7]
	v_mov_b64_e32 v[38:39], v[4:5]
	v_mov_b64_e32 v[36:37], v[2:3]
	v_mov_b64_e32 v[34:35], v[0:1]
	v_mov_b64_e32 v[30:31], v[12:13]
	v_mov_b64_e32 v[28:29], v[10:11]
	v_mov_b64_e32 v[26:27], v[8:9]
	v_mov_b64_e32 v[24:25], v[6:7]
	v_mov_b64_e32 v[22:23], v[4:5]
	v_mov_b64_e32 v[20:21], v[2:3]
	v_mov_b64_e32 v[18:19], v[0:1]
	v_mov_b64_e32 v[16:17], v[14:15]
	v_cmp_gt_i32_e64 s[12:13], 16, v197
	v_cmp_gt_i32_e64 s[14:15], 16, v198
	v_cmp_gt_i32_e64 s[16:17], 16, v199
	s_waitcnt vmcnt(11)
; #define MFMA32(a, b, c) __builtin_amdgcn_mfma_f32_32x32x16_bf16((a), (b), (c), 0, 0, 0)
; DI void phase_attn(int wid0, const Params& p, int L, unsigned char* lds, bool dry) {
;     ...
;         for (int t = 0; t < ntiles; ++t) {
;             asm volatile("s_waitcnt vmcnt(0) lgkmcnt(0)" ::: "memory"); __builtin_amdgcn_s_barrier(); asm volatile("" ::: "memory");
;             if (t + 1 < ntiles) attn_stage(kh_ + (size_t)(b * 4096 + 32 * t) * 2048, vh_ + (size_t)(b * 4096 + 32 * t) * 2048, koff, voff, ldsl + 65536 + ((t + 1) & 1) * 32768, wid);
;             const int kpos0 = (t == 0) ? 0 : 16 + 32 * (t - 1);
;             if (kpos0 <= wq0 + 31) {
;                 const unsigned char* Ks = lds + 65536 + (t & 1) * 32768 + psub * 8192;
;                 f32x16 p0, p0b;
; #pragma unroll
;                 for (int r = 0; r < 16; ++r) { p0[r] = 0.f; p0b[r] = 0.f; }
;                 int swz = (r32 & 6) << 4, kro = r32 * 256 + ((hi ^ (r32 & 1)) << 4); asm volatile("" : "+v"(swz), "+v"(kro));
; #pragma unroll
;                 for (int d0 = 0; d0 < 8; d0 += 2) {
;                     const bf16x8 b0 = *(const bf16x8*)(Ks + kro + ((d0 * 32) ^ swz));
;                     const bf16x8 qf = *(const bf16x8*)(qlds + d0 * 1024);
;                     const bf16x8 b1 = *(const bf16x8*)(Ks + kro + (((d0 + 1) * 32) ^ swz));
;                     const bf16x8 qg = *(const bf16x8*)(qlds + (d0 + 1) * 1024);
;                     p0 = MFMA32(b0, qf, p0);
;                     p0b = MFMA32(b1, qg, p0b);
;                     if (d0 == 2) __builtin_amdgcn_sched_barrier(0);
;                 }
; #pragma unroll
;                 for (int r = 0; r < 16; ++r) p0[r] += p0b[r];
;                 __builtin_amdgcn_sched_barrier(0);
;                 if (t > 0 && wq0 - (kpos0 + 31) >= 128) {
; #pragma unroll
;                     for (int r = 0; r < 16; ++r) p0[r] = fmaf(p0[r], ATT_C, bfar);
	v_mov_b32_e32 v182, v176
	v_mov_b32_e32 v183, v176
	s_add_i32 s39, s48, s39
	v_mov_b32_e32 v130, 0
	v_mov_b32_e32 v213, 0xf149f2ca
	s_mov_b32 s66, 0
	s_mov_b32 s100, 0
	s_mov_b32 s80, s40
	s_mov_b32 s81, 0
	s_lshl_b64 s[80:81], s[80:81], 12
	s_add_u32 s88, s84, s80
	s_addc_u32 s89, s85, s81
	s_add_u32 s92, s86, s80
	s_addc_u32 s93, s87, s81
	s_add_u32 s94, s92, 0x10000
	s_addc_u32 s95, s93, 0
	s_add_u32 s90, s88, 0x100
	s_addc_u32 s91, s89, 0
	s_add_i32 s96, s4, 0xffff0000
	v_mov_b32_e32 v132, 0
	v_mov_b32_e32 v133, 0
	v_mov_b32_e32 v134, 0
	v_mov_b32_e32 v135, 0
	v_mov_b32_e32 v136, 0
	v_mov_b32_e32 v137, 0
	v_mov_b32_e32 v138, 0
	v_mov_b32_e32 v139, 0
	s_lshl_b32 s80, s96, 1
	s_add_i32 s80, s80, 0xc000
	v_lshl_add_u32 v226, v190, 4, s80
	ds_write_b128 v226, v[132:135]
	ds_write_b128 v226, v[132:135] offset:1024
	v_add_u32_e32 v226, s5, v193
	v_add_u32_e32 v188, v226, v192
	v_xad_u32 v177, v192, 32, v226
	v_xad_u32 v209, v192, 64, v226
	s_movk_i32 s80, 0x60
	v_xad_u32 v210, v192, s80, v226
	s_movk_i32 s80, 0x80
	v_xad_u32 v211, v192, s80, v226
	s_movk_i32 s80, 0xa0
	v_xad_u32 v215, v192, s80, v226
	s_movk_i32 s80, 0xc0
	v_xad_u32 v224, v192, s80, v226
	s_movk_i32 s80, 0xe0
	v_xad_u32 v225, v192, s80, v226
	v_mov_b64_e32 v[14:15], v[12:13]
	v_mov_b64_e32 v[12:13], v[10:11]
	v_mov_b64_e32 v[10:11], v[8:9]
	v_mov_b64_e32 v[8:9], v[6:7]
	v_mov_b64_e32 v[6:7], v[4:5]
	v_mov_b64_e32 v[4:5], v[2:3]
	v_mov_b64_e32 v[2:3], v[0:1]
	s_mov_b32 s69, 0
.LBB0_99:
	s_waitcnt vmcnt(0) lgkmcnt(0)
	s_barrier
	s_add_i32 s67, s69, 1
	s_cmp_ge_i32 s67, s6
	s_cbranch_scc1 .Lattn_nodma0
	s_add_i32 m0, s4, 0x8000
	s_nop 0
	global_load_lds_dwordx4 v131, s[88:89]
	s_add_i32 m0, s4, 0xa000
	s_nop 0
	global_load_lds_dwordx4 v131, s[90:91]
	s_add_i32 m0, s96, 0x4000
	s_add_u32 s88, s88, 0x20000
	global_load_lds_dwordx4 v208, s[92:93]
	s_addc_u32 s89, s89, 0
	s_add_i32 m0, s96, 0x6000
	s_add_u32 s92, s92, 0x20000
	global_load_lds_dwordx4 v208, s[94:95]
	s_addc_u32 s93, s93, 0
	s_add_u32 s94, s94, 0x20000
	s_addc_u32 s95, s95, 0
	s_add_u32 s90, s90, 0x20000
	s_addc_u32 s91, s91, 0
.Lattn_nodma0:
	s_add_i32 s48, s7, -16
	s_cmp_lg_u32 s69, 0
	s_cselect_b32 s48, s48, 0
	s_cmp_gt_i32 s48, s38
	s_cbranch_scc1 .Lattn_skip0
	ds_read_b128 v[216:219], v188
	ds_read_b128 v[220:223], v177
	ds_read_b128 v[236:239], v209
	ds_read_b128 v[240:243], v210
	s_waitcnt lgkmcnt(3)
	v_mfma_f32_32x32x16_bf16 v[140:155], v[216:219], v[248:251], 0
	ds_read_b128 v[216:219], v211
	s_waitcnt lgkmcnt(3)
	v_mfma_f32_32x32x16_bf16 v[140:155], v[220:223], v[252:255], v[140:155]
	ds_read_b128 v[220:223], v215
	s_waitcnt lgkmcnt(3)
	v_mfma_f32_32x32x16_bf16 v[140:155], v[236:239], v[200:203], v[140:155]
	ds_read_b128 v[236:239], v224
	s_waitcnt lgkmcnt(3)
	v_mfma_f32_32x32x16_bf16 v[140:155], v[240:243], v[204:207], v[140:155]
	ds_read_b128 v[240:243], v225
	s_waitcnt lgkmcnt(3)
	v_mfma_f32_32x32x16_bf16 v[140:155], v[216:219], v[164:167], v[140:155]
	s_waitcnt lgkmcnt(2)
	v_mfma_f32_32x32x16_bf16 v[140:155], v[220:223], v[168:171], v[140:155]
	s_waitcnt lgkmcnt(1)
	v_mfma_f32_32x32x16_bf16 v[140:155], v[236:239], v[172:175], v[140:155]
	s_waitcnt lgkmcnt(0)
	v_mfma_f32_32x32x16_bf16 v[140:155], v[240:243], v[232:235], v[140:155]
	s_cmpk_gt_i32 s39, 0x7f
	s_cbranch_scc0 .Lattn_near0
	s_cmp_lg_u32 s69, 0
	s_cbranch_scc1 .Lattn_far0
; DI int crow(int r, int hi) { return (r & 3) + 8 * (r >> 2) + 4 * hi; }
; DI void phase_attn(int wid0, const Params& p, int L, unsigned char* lds, bool dry) {
;     ...
;                 } else {
; #pragma unroll
;                     for (int r = 0; r < 16; ++r) {
;                         const int k0i = crow(r, hi);
;                         const int d0v = qpos - (kpos0 + k0i);
;                         const bool v0 = (d0v >= 0) && (t > 0 || k0i < 16);
;                         const int idx = v0 ? (d0v < 128 ? d0v : 128) : 129;
;                         p0[r] = fmaf(p0[r], ATT_C, tab[idx]);
;                         if ((r & 3) == 3) __builtin_amdgcn_sched_barrier(0);
;                     }
;                 }
.Lattn_near0:
	s_cmp_lg_u32 s69, 0
	s_cselect_b64 s[80:81], -1, 0
	v_add_u32_e32 v226, s48, v194
	v_sub_u32_e32 v229, v195, v226
	v_sub_u32_e32 v216, v195, v226
	v_cmp_lt_i32_e32 vcc, -1, v216
	s_or_b64 s[82:83], s[10:11], s[80:81]
	v_add_u32_e32 v217, s48, v197
	v_min_i32_e32 v216, 0x80, v216
	s_and_b64 vcc, s[82:83], vcc
	v_sub_u32_e32 v217, v195, v217
	v_cndmask_b32_e32 v216, v187, v216, vcc
	v_cmp_lt_i32_e32 vcc, -1, v217
	s_or_b64 s[82:83], s[12:13], s[80:81]
	v_add_u32_e32 v218, s48, v198
	v_min_i32_e32 v217, 0x80, v217
	s_and_b64 vcc, s[82:83], vcc
	v_sub_u32_e32 v218, v195, v218
	v_cndmask_b32_e32 v217, v187, v217, vcc
	v_cmp_lt_i32_e32 vcc, -1, v218
	s_or_b64 s[82:83], s[14:15], s[80:81]
	v_add_u32_e32 v219, s48, v199
	v_min_i32_e32 v218, 0x80, v218
	s_and_b64 vcc, s[82:83], vcc
	v_sub_u32_e32 v219, v195, v219
	v_cndmask_b32_e32 v218, v187, v218, vcc
	v_cmp_lt_i32_e32 vcc, -1, v219
	s_or_b64 s[82:83], s[16:17], s[80:81]
	v_min_i32_e32 v219, 0x80, v219
	s_and_b64 vcc, s[82:83], vcc
	v_cndmask_b32_e32 v219, v187, v219, vcc
	v_lshl_add_u32 v216, v216, 2, s37
	v_lshl_add_u32 v217, v217, 2, s37
	v_lshl_add_u32 v218, v218, 2, s37
	v_lshl_add_u32 v219, v219, 2, s37
	ds_read_b32 v216, v216
	ds_read_b32 v217, v217
	ds_read_b32 v218, v218
	ds_read_b32 v219, v219
	v_add_u32_e32 v220, -8, v229
	v_cmp_lt_i32_e32 vcc, -1, v220
	s_or_b64 s[82:83], s[18:19], s[80:81]
	v_min_i32_e32 v220, 0x80, v220
	s_and_b64 vcc, s[82:83], vcc
	v_add_u32_e32 v221, -9, v229
	v_cndmask_b32_e32 v220, v187, v220, vcc
	v_cmp_lt_i32_e32 vcc, -1, v221
	v_min_i32_e32 v221, 0x80, v221
	s_and_b64 vcc, s[82:83], vcc
	v_add_u32_e32 v222, -10, v229
	v_cndmask_b32_e32 v221, v187, v221, vcc
	v_cmp_lt_i32_e32 vcc, -1, v222
	v_min_i32_e32 v222, 0x80, v222
	s_and_b64 vcc, s[82:83], vcc
	v_add_u32_e32 v223, -11, v229
	v_cndmask_b32_e32 v222, v187, v222, vcc
	v_cmp_lt_i32_e32 vcc, -1, v223
	v_min_i32_e32 v223, 0x80, v223
	s_and_b64 vcc, s[82:83], vcc
	v_cndmask_b32_e32 v223, v187, v223, vcc
	v_lshl_add_u32 v220, v220, 2, s37
	v_lshl_add_u32 v221, v221, 2, s37
	v_lshl_add_u32 v222, v222, 2, s37
	v_lshl_add_u32 v223, v223, 2, s37
	ds_read_b32 v220, v220
	ds_read_b32 v221, v221
	ds_read_b32 v222, v222
	ds_read_b32 v223, v223
	v_add_u32_e32 v236, -16, v229
	v_cmp_lt_i32_e32 vcc, -1, v236
	s_or_b64 s[82:83], s[20:21], s[80:81]
	v_min_i32_e32 v236, 0x80, v236
	s_and_b64 vcc, s[82:83], vcc
	v_add_u32_e32 v237, 0xffffffef, v229
	v_cndmask_b32_e32 v236, v187, v236, vcc
	v_cmp_lt_i32_e32 vcc, -1, v237
	v_min_i32_e32 v237, 0x80, v237
	s_and_b64 vcc, s[82:83], vcc
	v_add_u32_e32 v238, 0xffffffee, v229
	v_cndmask_b32_e32 v237, v187, v237, vcc
	v_cmp_lt_i32_e32 vcc, -1, v238
	v_min_i32_e32 v238, 0x80, v238
	s_and_b64 vcc, s[82:83], vcc
	v_add_u32_e32 v239, 0xffffffed, v229
	v_cndmask_b32_e32 v238, v187, v238, vcc
	v_cmp_lt_i32_e32 vcc, -1, v239
	v_min_i32_e32 v239, 0x80, v239
	s_and_b64 vcc, s[82:83], vcc
	v_cndmask_b32_e32 v239, v187, v239, vcc
	v_lshl_add_u32 v236, v236, 2, s37
	v_lshl_add_u32 v237, v237, 2, s37
	v_lshl_add_u32 v238, v238, 2, s37
	v_lshl_add_u32 v239, v239, 2, s37
	ds_read_b32 v236, v236
	ds_read_b32 v237, v237
	ds_read_b32 v238, v238
	ds_read_b32 v239, v239
	v_add_u32_e32 v240, 0xffffffe8, v229
	v_cmp_lt_i32_e32 vcc, -1, v240
	s_or_b64 s[80:81], s[22:23], s[80:81]
	v_min_i32_e32 v240, 0x80, v240
	s_and_b64 vcc, s[80:81], vcc
	v_add_u32_e32 v241, 0xffffffe7, v229
	v_cndmask_b32_e32 v240, v187, v240, vcc
	v_cmp_lt_i32_e32 vcc, -1, v241
	v_min_i32_e32 v241, 0x80, v241
	s_and_b64 vcc, s[80:81], vcc
	v_add_u32_e32 v242, 0xffffffe6, v229
	v_cndmask_b32_e32 v241, v187, v241, vcc
	v_cmp_lt_i32_e32 vcc, -1, v242
	v_min_i32_e32 v242, 0x80, v242
	s_and_b64 vcc, s[80:81], vcc
	v_add_u32_e32 v226, 0xffffffe5, v229
	v_cndmask_b32_e32 v242, v187, v242, vcc
	v_cmp_lt_i32_e32 vcc, -1, v226
	v_min_i32_e32 v226, 0x80, v226
	s_and_b64 vcc, s[80:81], vcc
	v_lshl_add_u32 v240, v240, 2, s37
	v_lshl_add_u32 v241, v241, 2, s37
	v_lshl_add_u32 v242, v242, 2, s37
	v_cndmask_b32_e32 v226, v187, v226, vcc
	v_lshl_add_u32 v226, v226, 2, s37
	ds_read_b32 v240, v240
	ds_read_b32 v241, v241
	ds_read_b32 v242, v242
	ds_read_b32 v243, v226
	s_waitcnt lgkmcnt(0)
	v_pk_fma_f32 v[140:141], v[140:141], s[36:37], v[216:217] op_sel_hi:[1,0,1]
	v_pk_fma_f32 v[142:143], v[142:143], s[36:37], v[218:219] op_sel_hi:[1,0,1]
	v_pk_fma_f32 v[144:145], v[144:145], s[36:37], v[220:221] op_sel_hi:[1,0,1]
	v_pk_fma_f32 v[146:147], v[146:147], s[36:37], v[222:223] op_sel_hi:[1,0,1]
	v_pk_fma_f32 v[148:149], v[148:149], s[36:37], v[236:237] op_sel_hi:[1,0,1]
	v_pk_fma_f32 v[150:151], v[150:151], s[36:37], v[238:239] op_sel_hi:[1,0,1]
	v_pk_fma_f32 v[152:153], v[152:153], s[36:37], v[240:241] op_sel_hi:[1,0,1]
	v_pk_fma_f32 v[154:155], v[154:155], s[36:37], v[242:243] op_sel_hi:[1,0,1]
	s_mov_b32 s82, 1.0
	v_mov_b32_e32 v231, 0
	s_branch .Lattn_region0

; DI void phase_attn(int wid0, const Params& p, int L, unsigned char* lds, bool dry) {
;     ...
;                 float pmax = p0[0];
; #pragma unroll
;                 for (int r = 1; r < 16; ++r) pmax = fmaxf(pmax, p0[r]);
;                 { auto rr = __builtin_amdgcn_permlane32_swap(__float_as_uint(pmax), __float_as_uint(pmax), false, false); pmax = fmaxf(__uint_as_float(rr[0]), __uint_as_float(rr[1])); }
;                 float mn, alpha;
;                 if (__all(pmax - m_reg <= ATT_THR2)) { mn = m_reg; alpha = 1.f; }
;                 else { mn = fmaxf(m_reg, pmax); alpha = __builtin_amdgcn_exp2f(m_reg - mn); m_reg = mn; }
;                 float ps = 0.f;
; #pragma unroll
;                 for (int r = 0; r < 16; ++r) { p0[r] = __builtin_amdgcn_exp2f(p0[r] - mn); ps += p0[r]; }
;                 { auto rr = __builtin_amdgcn_permlane32_swap(__float_as_uint(ps), __float_as_uint(ps), false, false); ps = __uint_as_float(rr[0]) + __uint_as_float(rr[1]); }
;                 l_reg = l_reg * alpha + ps;
;                 __builtin_amdgcn_sched_barrier(0);
;                 bf16x8 pa0, pa1;
;     ...
;                 PK4(p0, 0, pa0); PK4(p0, 8, pa1);
;     ...
;                 __builtin_amdgcn_sched_barrier(0);
;                 if (__any(alpha < 1.f)) {
;                     if (hi == 0) al_l[r32] = alpha;
;                     asm volatile("s_waitcnt lgkmcnt(0)" ::: "memory");
;                     float ar[16];
; #pragma unroll
;                     for (int r = 0; r < 16; ++r) ar[r] = al_l[crow(r, hi)];
; #pragma unroll
;                     for (int d = 0; d < 8; ++d)
; #pragma unroll
;                         for (int r = 0; r < 16; ++r) o[d][r] *= ar[r];
;                 }
;                 __builtin_amdgcn_sched_barrier(0);
;                 LAS unsigned char* vbp = ldsl + 65536 + (t & 1) * 32768 + 16384 + v_rd_base(lane);
;                 __builtin_amdgcn_s_setprio(1);
;     ...
;                 {
;                     s16x4 a0, a1, a2, a3, b0_, b1_, b2_, b3_;
;                     PV_RD(0, a0, a1, a2, a3); SB();
;                     PV_RD(1, b0_, b1_, b2_, b3_); SB(); PV_MM(0, a0, a1, a2, a3); SB();
;                     PV_RD(2, a0, a1, a2, a3); SB(); PV_MM(1, b0_, b1_, b2_, b3_); SB();
;                     PV_RD(3, b0_, b1_, b2_, b3_); SB(); PV_MM(2, a0, a1, a2, a3); SB();
;                     PV_RD(4, a0, a1, a2, a3); SB(); PV_MM(3, b0_, b1_, b2_, b3_); SB();
.Lattn_region0:
	ds_read_b64_tr_b16 v[216:217], v212 offset:49152
	ds_read_b64_tr_b16 v[218:219], v212 offset:53248
	ds_read_b64_tr_b16 v[220:221], v212 offset:57344
	ds_read_b64_tr_b16 v[222:223], v212 offset:61440
	ds_read_b64_tr_b16 v[236:237], v212 offset:49664
	ds_read_b64_tr_b16 v[238:239], v212 offset:53760
	ds_read_b64_tr_b16 v[240:241], v212 offset:57856
	ds_read_b64_tr_b16 v[242:243], v212 offset:61952
	s_waitcnt lgkmcnt(6)
	v_mfma_f32_32x32x16_bf16 v[114:129], v[132:135], v[216:219], v[114:129]
	s_waitcnt lgkmcnt(4)
	v_mfma_f32_32x32x16_bf16 v[114:129], v[136:139], v[220:223], v[114:129]
	v_max3_f32 v226, v140, v141, v142
	v_max3_f32 v226, v226, v143, v144
	v_max3_f32 v226, v226, v145, v146
	v_max3_f32 v226, v226, v147, v148
	v_max3_f32 v226, v226, v149, v150
	v_max3_f32 v226, v226, v151, v152
	v_max3_f32 v226, v226, v153, v154
	ds_read_b64_tr_b16 v[216:217], v212 offset:50176
	ds_read_b64_tr_b16 v[218:219], v212 offset:54272
	ds_read_b64_tr_b16 v[220:221], v212 offset:58368
	ds_read_b64_tr_b16 v[222:223], v212 offset:62464
	s_waitcnt lgkmcnt(6)
	v_mfma_f32_32x32x16_bf16 v[98:113], v[132:135], v[236:239], v[98:113]
	v_max_f32_e32 v226, v226, v155
	v_mov_b32_e32 v227, v226
	s_nop 1
	v_permlane32_swap_b32_e32 v226, v227
	v_max_f32_e32 v226, v226, v227
	v_fma_f32 v226, v226, s82, v231
	v_sub_f32_e32 v227, v226, v213
	s_mov_b32 s48, 0x4138aa3b
	s_waitcnt lgkmcnt(4)
	v_mfma_f32_32x32x16_bf16 v[98:113], v[136:139], v[240:243], v[98:113]
	v_cmp_ge_f32_e32 vcc, s48, v227
	s_cmp_eq_u64 vcc, exec
	v_max_f32_e32 v226, v213, v226
	s_cselect_b64 vcc, -1, 0
	v_sub_f32_e32 v227, v213, v226
	v_cndmask_b32_e32 v213, v226, v213, vcc
	v_sub_f32_e32 v230, v231, v213
	v_fma_f32 v140, v140, s82, v230
	ds_read_b64_tr_b16 v[236:237], v212 offset:50688
	ds_read_b64_tr_b16 v[238:239], v212 offset:54784
	ds_read_b64_tr_b16 v[240:241], v212 offset:58880
	ds_read_b64_tr_b16 v[242:243], v212 offset:62976
	s_waitcnt lgkmcnt(6)
	v_mfma_f32_32x32x16_bf16 v[82:97], v[132:135], v[216:219], v[82:97]
	v_exp_f32_e32 v140, v140
	v_fma_f32 v141, v141, s82, v230
	v_exp_f32_e32 v141, v141
	v_fma_f32 v142, v142, s82, v230
	v_exp_f32_e32 v142, v142
	s_waitcnt lgkmcnt(4)
	v_mfma_f32_32x32x16_bf16 v[82:97], v[136:139], v[220:223], v[82:97]
	v_add_f32_e32 v226, v140, v141
	v_fma_f32 v143, v143, s82, v230
	v_exp_f32_e32 v143, v143
	v_add_f32_e32 v226, v226, v142
	v_fma_f32 v144, v144, s82, v230
	v_exp_f32_e32 v144, v144
	ds_read_b64_tr_b16 v[216:217], v212 offset:51200
	ds_read_b64_tr_b16 v[218:219], v212 offset:55296
	ds_read_b64_tr_b16 v[220:221], v212 offset:59392
	ds_read_b64_tr_b16 v[222:223], v212 offset:63488
	s_waitcnt lgkmcnt(6)
	v_mfma_f32_32x32x16_bf16 v[66:81], v[132:135], v[236:239], v[66:81]
	v_add_f32_e32 v226, v226, v143
	v_fma_f32 v145, v145, s82, v230
	v_exp_f32_e32 v145, v145
	v_add_f32_e32 v226, v226, v144
	v_fma_f32 v146, v146, s82, v230
	v_exp_f32_e32 v146, v146
	s_waitcnt lgkmcnt(4)
	v_mfma_f32_32x32x16_bf16 v[66:81], v[136:139], v[240:243], v[66:81]
	v_add_f32_e32 v226, v226, v145
	v_fma_f32 v147, v147, s82, v230
	v_exp_f32_e32 v147, v147
	v_add_f32_e32 v226, v226, v146
	v_fma_f32 v148, v148, s82, v230
	v_exp_f32_e32 v148, v148
	ds_read_b64_tr_b16 v[236:237], v212 offset:51712
	ds_read_b64_tr_b16 v[238:239], v212 offset:55808
	ds_read_b64_tr_b16 v[240:241], v212 offset:59904
	ds_read_b64_tr_b16 v[242:243], v212 offset:64000
	s_waitcnt lgkmcnt(6)
	v_mfma_f32_32x32x16_bf16 v[50:65], v[132:135], v[216:219], v[50:65]
	v_add_f32_e32 v226, v226, v147
	v_fma_f32 v149, v149, s82, v230
	v_exp_f32_e32 v149, v149
	v_add_f32_e32 v226, v226, v148
	v_fma_f32 v150, v150, s82, v230
	v_exp_f32_e32 v150, v150
	s_waitcnt lgkmcnt(4)
	v_mfma_f32_32x32x16_bf16 v[50:65], v[136:139], v[220:223], v[50:65]
	v_add_f32_e32 v226, v226, v149
	v_fma_f32 v151, v151, s82, v230
	v_exp_f32_e32 v151, v151
	v_add_f32_e32 v226, v226, v150
	v_fma_f32 v152, v152, s82, v230
	ds_read_b64_tr_b16 v[216:217], v212 offset:52224
	ds_read_b64_tr_b16 v[218:219], v212 offset:56320
	ds_read_b64_tr_b16 v[220:221], v212 offset:60416
	ds_read_b64_tr_b16 v[222:223], v212 offset:64512
	s_waitcnt lgkmcnt(6)
	v_mfma_f32_32x32x16_bf16 v[34:49], v[132:135], v[236:239], v[34:49]
	v_exp_f32_e32 v152, v152
	v_add_f32_e32 v226, v226, v151
	v_fma_f32 v153, v153, s82, v230
	v_exp_f32_e32 v153, v153
	s_waitcnt lgkmcnt(4)
	v_mfma_f32_32x32x16_bf16 v[34:49], v[136:139], v[240:243], v[34:49]
	v_add_f32_e32 v226, v226, v152
	v_fma_f32 v154, v154, s82, v230
	v_exp_f32_e32 v154, v154
	v_add_f32_e32 v226, v226, v153
	v_fma_f32 v155, v155, s82, v230
	ds_read_b64_tr_b16 v[236:237], v212 offset:52736
	ds_read_b64_tr_b16 v[238:239], v212 offset:56832
	ds_read_b64_tr_b16 v[240:241], v212 offset:60928
	ds_read_b64_tr_b16 v[242:243], v212 offset:65024
	s_waitcnt lgkmcnt(6)
	v_mfma_f32_32x32x16_bf16 v[18:33], v[132:135], v[216:219], v[18:33]
	v_exp_f32_e32 v155, v155
	v_add_f32_e32 v226, v226, v154
	v_exp_f32_e32 v227, v227
	v_add_f32_e32 v228, v226, v155
	s_waitcnt lgkmcnt(4)
	v_mfma_f32_32x32x16_bf16 v[18:33], v[136:139], v[220:223], v[18:33]
	v_cndmask_b32_e64 v227, v227, 1.0, vcc
	v_mov_b32_e32 v229, v228
	v_cvt_pk_bf16_f32 v156, v140, v141
	v_cvt_pk_bf16_f32 v157, v142, v143
	v_cvt_pk_bf16_f32 v158, v144, v145
	v_cvt_pk_bf16_f32 v159, v146, v147
	s_waitcnt lgkmcnt(2)
	v_mfma_f32_32x32x16_bf16 v[2:17], v[132:135], v[236:239], v[2:17]
	v_cvt_pk_bf16_f32 v160, v148, v149
	v_cvt_pk_bf16_f32 v161, v150, v151
	v_cvt_pk_bf16_f32 v162, v152, v153
	v_cvt_pk_bf16_f32 v163, v154, v155
	v_permlane32_swap_b32_e32 v228, v229
	v_permlane32_swap_b32_e32 v156, v158
	s_waitcnt lgkmcnt(0)
	v_mfma_f32_32x32x16_bf16 v[2:17], v[136:139], v[240:243], v[2:17]
	v_permlane32_swap_b32_e32 v157, v159
	v_permlane32_swap_b32_e32 v160, v162
	v_permlane32_swap_b32_e32 v161, v163
	v_add_f32_e32 v228, v228, v229
	v_fma_f32 v130, v130, v227, v228
	v_cmp_gt_f32_e32 vcc, 1.0, v227
	s_cbranch_vccz .Lattn_norescale0
; DI int crow(int r, int hi) { return (r & 3) + 8 * (r >> 2) + 4 * hi; }
; DI void phase_attn(int wid0, const Params& p, int L, unsigned char* lds, bool dry) {
;     ...
;                 if (__any(alpha < 1.f)) {
;                     if (hi == 0) al_l[r32] = alpha;
;                     asm volatile("s_waitcnt lgkmcnt(0)" ::: "memory");
;                     float ar[16];
; #pragma unroll
;                     for (int r = 0; r < 16; ++r) ar[r] = al_l[crow(r, hi)];
; #pragma unroll
;                     for (int d = 0; d < 8; ++d)
; #pragma unroll
;                         for (int r = 0; r < 16; ++r) o[d][r] *= ar[r];
;                 }
	s_and_saveexec_b64 s[80:81], s[8:9]
	ds_write_b32 v196, v227 offset:128
	s_or_b64 exec, exec, s[80:81]
	s_waitcnt lgkmcnt(0)
	ds_read_b128 v[152:155], v214 offset:224
	ds_read_b128 v[148:151], v214 offset:192
	ds_read_b128 v[144:147], v214 offset:160
	ds_read_b128 v[140:143], v214 offset:128
	s_waitcnt lgkmcnt(0)
	v_pk_mul_f32 v[126:127], v[126:127], v[152:153]
	v_pk_mul_f32 v[122:123], v[122:123], v[148:149]
	v_pk_mul_f32 v[118:119], v[118:119], v[144:145]
	v_pk_mul_f32 v[128:129], v[128:129], v[154:155]
	v_pk_mul_f32 v[124:125], v[124:125], v[150:151]
	v_pk_mul_f32 v[120:121], v[120:121], v[146:147]
	v_pk_mul_f32 v[116:117], v[116:117], v[142:143]
	v_pk_mul_f32 v[114:115], v[114:115], v[140:141]
	v_pk_mul_f32 v[110:111], v[110:111], v[152:153]
	v_pk_mul_f32 v[106:107], v[106:107], v[148:149]
	v_pk_mul_f32 v[102:103], v[102:103], v[144:145]
	v_pk_mul_f32 v[112:113], v[112:113], v[154:155]
	v_pk_mul_f32 v[108:109], v[108:109], v[150:151]
	v_pk_mul_f32 v[104:105], v[104:105], v[146:147]
	v_pk_mul_f32 v[100:101], v[100:101], v[142:143]
	v_pk_mul_f32 v[98:99], v[98:99], v[140:141]
	v_pk_mul_f32 v[94:95], v[94:95], v[152:153]
	v_pk_mul_f32 v[90:91], v[90:91], v[148:149]
	v_pk_mul_f32 v[86:87], v[86:87], v[144:145]
	v_pk_mul_f32 v[96:97], v[96:97], v[154:155]
	v_pk_mul_f32 v[92:93], v[92:93], v[150:151]
	v_pk_mul_f32 v[88:89], v[88:89], v[146:147]
	v_pk_mul_f32 v[84:85], v[84:85], v[142:143]
	v_pk_mul_f32 v[82:83], v[82:83], v[140:141]
	v_pk_mul_f32 v[78:79], v[78:79], v[152:153]
	v_pk_mul_f32 v[74:75], v[74:75], v[148:149]
	v_pk_mul_f32 v[70:71], v[70:71], v[144:145]
	v_pk_mul_f32 v[80:81], v[80:81], v[154:155]
	v_pk_mul_f32 v[76:77], v[76:77], v[150:151]
	v_pk_mul_f32 v[72:73], v[72:73], v[146:147]
	v_pk_mul_f32 v[68:69], v[68:69], v[142:143]
	v_pk_mul_f32 v[66:67], v[66:67], v[140:141]
	v_pk_mul_f32 v[62:63], v[62:63], v[152:153]
	v_pk_mul_f32 v[58:59], v[58:59], v[148:149]
	v_pk_mul_f32 v[54:55], v[54:55], v[144:145]
	v_pk_mul_f32 v[64:65], v[64:65], v[154:155]
	v_pk_mul_f32 v[60:61], v[60:61], v[150:151]
	v_pk_mul_f32 v[56:57], v[56:57], v[146:147]
	v_pk_mul_f32 v[52:53], v[52:53], v[142:143]
	v_pk_mul_f32 v[50:51], v[50:51], v[140:141]
	v_pk_mul_f32 v[46:47], v[46:47], v[152:153]
	v_pk_mul_f32 v[42:43], v[42:43], v[148:149]
	v_pk_mul_f32 v[38:39], v[38:39], v[144:145]
	v_pk_mul_f32 v[48:49], v[48:49], v[154:155]
	v_pk_mul_f32 v[44:45], v[44:45], v[150:151]
	v_pk_mul_f32 v[40:41], v[40:41], v[146:147]
	v_pk_mul_f32 v[36:37], v[36:37], v[142:143]
	v_pk_mul_f32 v[34:35], v[34:35], v[140:141]
	v_pk_mul_f32 v[30:31], v[30:31], v[152:153]
	v_pk_mul_f32 v[26:27], v[26:27], v[148:149]
	v_pk_mul_f32 v[22:23], v[22:23], v[144:145]
	v_pk_mul_f32 v[32:33], v[32:33], v[154:155]
	v_pk_mul_f32 v[28:29], v[28:29], v[150:151]
	v_pk_mul_f32 v[24:25], v[24:25], v[146:147]
	v_pk_mul_f32 v[20:21], v[20:21], v[142:143]
	v_pk_mul_f32 v[18:19], v[18:19], v[140:141]
	v_pk_mul_f32 v[14:15], v[14:15], v[152:153]
	v_pk_mul_f32 v[10:11], v[10:11], v[148:149]
	v_pk_mul_f32 v[6:7], v[6:7], v[144:145]
	v_pk_mul_f32 v[16:17], v[16:17], v[154:155]
	v_pk_mul_f32 v[12:13], v[12:13], v[150:151]
	v_pk_mul_f32 v[8:9], v[8:9], v[146:147]
	v_pk_mul_f32 v[4:5], v[4:5], v[142:143]
	v_pk_mul_f32 v[2:3], v[2:3], v[140:141]

; DI void phase_attn(int wid0, const Params& p, int L, unsigned char* lds, bool dry) {
;     ...
;         for (int t = 0; t < ntiles; ++t) {
;             asm volatile("s_waitcnt vmcnt(0) lgkmcnt(0)" ::: "memory"); __builtin_amdgcn_s_barrier(); asm volatile("" ::: "memory");
;             if (t + 1 < ntiles) attn_stage(kh_ + (size_t)(b * 4096 + 32 * t) * 2048, vh_ + (size_t)(b * 4096 + 32 * t) * 2048, koff, voff, ldsl + 65536 + ((t + 1) & 1) * 32768, wid);
;             const int kpos0 = (t == 0) ? 0 : 16 + 32 * (t - 1);
;             if (kpos0 <= wq0 + 31) {
;                 const unsigned char* Ks = lds + 65536 + (t & 1) * 32768 + psub * 8192;
;                 f32x16 p0, p0b;
; #pragma unroll
;                 for (int r = 0; r < 16; ++r) { p0[r] = 0.f; p0b[r] = 0.f; }
;                 int swz = (r32 & 6) << 4, kro = r32 * 256 + ((hi ^ (r32 & 1)) << 4); asm volatile("" : "+v"(swz), "+v"(kro));
; #pragma unroll
;                 for (int d0 = 0; d0 < 8; d0 += 2) {
;                     const bf16x8 b0 = *(const bf16x8*)(Ks + kro + ((d0 * 32) ^ swz));
;                     const bf16x8 qf = *(const bf16x8*)(qlds + d0 * 1024);
;                     const bf16x8 b1 = *(const bf16x8*)(Ks + kro + (((d0 + 1) * 32) ^ swz));
;                     const bf16x8 qg = *(const bf16x8*)(qlds + (d0 + 1) * 1024);
;                     p0 = MFMA32(b0, qf, p0);
;     ...
;                 LAS unsigned char* vbp = ldsl + 65536 + (t & 1) * 32768 + 16384 + v_rd_base(lane);
;                 __builtin_amdgcn_s_setprio(1);
;     ...
;                 {
;                     s16x4 a0, a1, a2, a3, b0_, b1_, b2_, b3_;
;                     PV_RD(0, a0, a1, a2, a3); SB();
;                     PV_RD(1, b0_, b1_, b2_, b3_); SB(); PV_MM(0, a0, a1, a2, a3); SB();
;                     PV_RD(2, a0, a1, a2, a3); SB(); PV_MM(1, b0_, b1_, b2_, b3_); SB();
;                     PV_RD(3, b0_, b1_, b2_, b3_); SB(); PV_MM(2, a0, a1, a2, a3); SB();
;                     PV_RD(4, a0, a1, a2, a3); SB(); PV_MM(3, b0_, b1_, b2_, b3_); SB();
;                     PV_RD(5, b0_, b1_, b2_, b3_); SB(); PV_MM(4, a0, a1, a2, a3); SB();
;                     PV_RD(6, a0, a1, a2, a3); SB(); PV_MM(5, b0_, b1_, b2_, b3_); SB();
;                     PV_RD(7, b0_, b1_, b2_, b3_); SB(); PV_MM(6, a0, a1, a2, a3); SB();
;                     PV_MM(7, b0_, b1_, b2_, b3_); SB();
;                 }
.Lattn_pvplain3:
	s_setprio 1
	ds_read_b64_tr_b16 v[140:141], v212 offset:49152
	ds_read_b64_tr_b16 v[142:143], v212 offset:53248
	ds_read_b64_tr_b16 v[144:145], v212 offset:57344
	ds_read_b64_tr_b16 v[146:147], v212 offset:61440
	ds_read_b64_tr_b16 v[148:149], v212 offset:49664
	ds_read_b64_tr_b16 v[150:151], v212 offset:53760
	ds_read_b64_tr_b16 v[152:153], v212 offset:57856
	ds_read_b64_tr_b16 v[154:155], v212 offset:61952
	s_waitcnt lgkmcnt(6)
	v_mfma_f32_32x32x16_bf16 v[114:129], v[132:135], v[140:143], v[114:129]
	s_waitcnt lgkmcnt(4)
	v_mfma_f32_32x32x16_bf16 v[114:129], v[136:139], v[144:147], v[114:129]
	ds_read_b64_tr_b16 v[140:141], v212 offset:50176
	ds_read_b64_tr_b16 v[142:143], v212 offset:54272
	ds_read_b64_tr_b16 v[144:145], v212 offset:58368
	ds_read_b64_tr_b16 v[146:147], v212 offset:62464
	s_waitcnt lgkmcnt(6)
	v_mfma_f32_32x32x16_bf16 v[98:113], v[132:135], v[148:151], v[98:113]
	s_waitcnt lgkmcnt(4)
	v_mfma_f32_32x32x16_bf16 v[98:113], v[136:139], v[152:155], v[98:113]
	ds_read_b64_tr_b16 v[148:149], v212 offset:50688
	ds_read_b64_tr_b16 v[150:151], v212 offset:54784
	ds_read_b64_tr_b16 v[152:153], v212 offset:58880
	ds_read_b64_tr_b16 v[154:155], v212 offset:62976
	s_waitcnt lgkmcnt(6)
	v_mfma_f32_32x32x16_bf16 v[82:97], v[132:135], v[140:143], v[82:97]
	s_waitcnt lgkmcnt(4)
	v_mfma_f32_32x32x16_bf16 v[82:97], v[136:139], v[144:147], v[82:97]
	ds_read_b64_tr_b16 v[140:141], v212 offset:51200
	ds_read_b64_tr_b16 v[142:143], v212 offset:55296
	ds_read_b64_tr_b16 v[144:145], v212 offset:59392
	ds_read_b64_tr_b16 v[146:147], v212 offset:63488
	s_waitcnt lgkmcnt(6)
	v_mfma_f32_32x32x16_bf16 v[66:81], v[132:135], v[148:151], v[66:81]
	s_waitcnt lgkmcnt(4)
	v_mfma_f32_32x32x16_bf16 v[66:81], v[136:139], v[152:155], v[66:81]
	ds_read_b64_tr_b16 v[148:149], v212 offset:51712
	ds_read_b64_tr_b16 v[150:151], v212 offset:55808
	ds_read_b64_tr_b16 v[152:153], v212 offset:59904
	ds_read_b64_tr_b16 v[154:155], v212 offset:64000
	s_waitcnt lgkmcnt(6)
	v_mfma_f32_32x32x16_bf16 v[50:65], v[132:135], v[140:143], v[50:65]
	s_waitcnt lgkmcnt(4)
	v_mfma_f32_32x32x16_bf16 v[50:65], v[136:139], v[144:147], v[50:65]
	ds_read_b64_tr_b16 v[140:141], v212 offset:52224
	ds_read_b64_tr_b16 v[142:143], v212 offset:56320
	ds_read_b64_tr_b16 v[144:145], v212 offset:60416
	ds_read_b64_tr_b16 v[146:147], v212 offset:64512
	s_waitcnt lgkmcnt(6)
	v_mfma_f32_32x32x16_bf16 v[34:49], v[132:135], v[148:151], v[34:49]
	s_waitcnt lgkmcnt(4)
	v_mfma_f32_32x32x16_bf16 v[34:49], v[136:139], v[152:155], v[34:49]
	ds_read_b64_tr_b16 v[148:149], v212 offset:52736
	ds_read_b64_tr_b16 v[150:151], v212 offset:56832
	ds_read_b64_tr_b16 v[152:153], v212 offset:60928
	ds_read_b64_tr_b16 v[154:155], v212 offset:65024
	s_waitcnt lgkmcnt(6)
	v_mfma_f32_32x32x16_bf16 v[18:33], v[132:135], v[140:143], v[18:33]
	s_waitcnt lgkmcnt(4)
	v_mfma_f32_32x32x16_bf16 v[18:33], v[136:139], v[144:147], v[18:33]
	s_waitcnt lgkmcnt(2)
	v_mfma_f32_32x32x16_bf16 v[2:17], v[132:135], v[148:151], v[2:17]
	s_waitcnt lgkmcnt(0)
	v_mfma_f32_32x32x16_bf16 v[2:17], v[136:139], v[152:155], v[2:17]
	s_setprio 0
	s_andn2_b32 s100, s100, 0x100
	s_bitcmp1_b32 s100, 9
	s_cbranch_scc1 .LBB0_113
.Lattn_latch0:
	s_sub_i32 s39, s39, 32
	s_add_i32 s7, s7, 32
	s_cmp_eq_u32 s6, s67
	s_cbranch_scc1 .Lattn_exit0
	s_mov_b32 s69, s67
.Lattn_top1:
	s_waitcnt vmcnt(0) lgkmcnt(0)
	s_barrier
	s_add_i32 s67, s69, 1
	s_cmp_ge_i32 s67, s6
	s_cbranch_scc1 .Lattn_nodma1
	s_add_i32 m0, s4, 0x0
	s_nop 0
	global_load_lds_dwordx4 v131, s[88:89]
	s_add_i32 m0, s4, 0x2000
	s_nop 0
	global_load_lds_dwordx4 v131, s[90:91]
	s_add_i32 m0, s96, 0x8000
	s_add_u32 s88, s88, 0x20000
	global_load_lds_dwordx4 v208, s[92:93]
	s_addc_u32 s89, s89, 0
	s_add_i32 m0, s96, 0xa000
	s_add_u32 s92, s92, 0x20000
	global_load_lds_dwordx4 v208, s[94:95]
	s_addc_u32 s93, s93, 0
	s_add_u32 s94, s94, 0x20000
	s_addc_u32 s95, s95, 0
	s_add_u32 s90, s90, 0x20000
	s_addc_u32 s91, s91, 0
.Lattn_nodma1:
	s_add_i32 s48, s7, -16
	s_cmp_lg_u32 s69, 0
	s_cselect_b32 s48, s48, 0
	s_cmp_gt_i32 s48, s38
	s_cbranch_scc1 .Lattn_skip1
	ds_read_b128 v[216:219], v188 offset:32768
	ds_read_b128 v[220:223], v177 offset:32768
	ds_read_b128 v[236:239], v209 offset:32768
	ds_read_b128 v[240:243], v210 offset:32768
	s_waitcnt lgkmcnt(3)
	v_mfma_f32_32x32x16_bf16 v[140:155], v[216:219], v[248:251], 0
	ds_read_b128 v[216:219], v211 offset:32768
	s_waitcnt lgkmcnt(3)
	v_mfma_f32_32x32x16_bf16 v[140:155], v[220:223], v[252:255], v[140:155]
	ds_read_b128 v[220:223], v215 offset:32768
	s_waitcnt lgkmcnt(3)
	v_mfma_f32_32x32x16_bf16 v[140:155], v[236:239], v[200:203], v[140:155]
	ds_read_b128 v[236:239], v224 offset:32768
	s_waitcnt lgkmcnt(3)
	v_mfma_f32_32x32x16_bf16 v[140:155], v[240:243], v[204:207], v[140:155]
	ds_read_b128 v[240:243], v225 offset:32768
	s_waitcnt lgkmcnt(3)
	v_mfma_f32_32x32x16_bf16 v[140:155], v[216:219], v[164:167], v[140:155]
	s_waitcnt lgkmcnt(2)
	v_mfma_f32_32x32x16_bf16 v[140:155], v[220:223], v[168:171], v[140:155]
	s_waitcnt lgkmcnt(1)
	v_mfma_f32_32x32x16_bf16 v[140:155], v[236:239], v[172:175], v[140:155]
	s_waitcnt lgkmcnt(0)
	v_mfma_f32_32x32x16_bf16 v[140:155], v[240:243], v[232:235], v[140:155]
	s_cmpk_gt_i32 s39, 0x7f
	s_cbranch_scc0 .Lattn_near1
	s_cmp_lg_u32 s69, 0
	s_cbranch_scc1 .Lattn_far1

; DI void phase_attn(int wid0, const Params& p, int L, unsigned char* lds, bool dry) {
;     ...
;                 float pmax = p0[0];
; #pragma unroll
;                 for (int r = 1; r < 16; ++r) pmax = fmaxf(pmax, p0[r]);
;                 { auto rr = __builtin_amdgcn_permlane32_swap(__float_as_uint(pmax), __float_as_uint(pmax), false, false); pmax = fmaxf(__uint_as_float(rr[0]), __uint_as_float(rr[1])); }
;                 float mn, alpha;
;                 if (__all(pmax - m_reg <= ATT_THR2)) { mn = m_reg; alpha = 1.f; }
;                 else { mn = fmaxf(m_reg, pmax); alpha = __builtin_amdgcn_exp2f(m_reg - mn); m_reg = mn; }
;                 float ps = 0.f;
; #pragma unroll
;                 for (int r = 0; r < 16; ++r) { p0[r] = __builtin_amdgcn_exp2f(p0[r] - mn); ps += p0[r]; }
;                 { auto rr = __builtin_amdgcn_permlane32_swap(__float_as_uint(ps), __float_as_uint(ps), false, false); ps = __uint_as_float(rr[0]) + __uint_as_float(rr[1]); }
;                 l_reg = l_reg * alpha + ps;
;                 __builtin_amdgcn_sched_barrier(0);
;                 bf16x8 pa0, pa1;
;     ...
;                 PK4(p0, 0, pa0); PK4(p0, 8, pa1);
;     ...
;                 __builtin_amdgcn_sched_barrier(0);
;                 if (__any(alpha < 1.f)) {
;                     if (hi == 0) al_l[r32] = alpha;
;                     asm volatile("s_waitcnt lgkmcnt(0)" ::: "memory");
;                     float ar[16];
; #pragma unroll
;                     for (int r = 0; r < 16; ++r) ar[r] = al_l[crow(r, hi)];
; #pragma unroll
;                     for (int d = 0; d < 8; ++d)
; #pragma unroll
;                         for (int r = 0; r < 16; ++r) o[d][r] *= ar[r];
;                 }
;                 __builtin_amdgcn_sched_barrier(0);
;                 LAS unsigned char* vbp = ldsl + 65536 + (t & 1) * 32768 + 16384 + v_rd_base(lane);
;                 __builtin_amdgcn_s_setprio(1);
;     ...
;                 {
;                     s16x4 a0, a1, a2, a3, b0_, b1_, b2_, b3_;
;                     PV_RD(0, a0, a1, a2, a3); SB();
;                     PV_RD(1, b0_, b1_, b2_, b3_); SB(); PV_MM(0, a0, a1, a2, a3); SB();
;                     PV_RD(2, a0, a1, a2, a3); SB(); PV_MM(1, b0_, b1_, b2_, b3_); SB();
;                     PV_RD(3, b0_, b1_, b2_, b3_); SB(); PV_MM(2, a0, a1, a2, a3); SB();
;                     PV_RD(4, a0, a1, a2, a3); SB(); PV_MM(3, b0_, b1_, b2_, b3_); SB();
.Lattn_region1:
	ds_read_b64_tr_b16 v[216:217], v212 offset:0
	ds_read_b64_tr_b16 v[218:219], v212 offset:4096
	ds_read_b64_tr_b16 v[220:221], v212 offset:8192
	ds_read_b64_tr_b16 v[222:223], v212 offset:12288
	ds_read_b64_tr_b16 v[236:237], v212 offset:512
	ds_read_b64_tr_b16 v[238:239], v212 offset:4608
	ds_read_b64_tr_b16 v[240:241], v212 offset:8704
	ds_read_b64_tr_b16 v[242:243], v212 offset:12800
	s_waitcnt lgkmcnt(6)
	v_mfma_f32_32x32x16_bf16 v[114:129], v[156:159], v[216:219], v[114:129]
	s_waitcnt lgkmcnt(4)
	v_mfma_f32_32x32x16_bf16 v[114:129], v[160:163], v[220:223], v[114:129]
	v_max3_f32 v226, v140, v141, v142
	v_max3_f32 v226, v226, v143, v144
	v_max3_f32 v226, v226, v145, v146
	v_max3_f32 v226, v226, v147, v148
	v_max3_f32 v226, v226, v149, v150
	v_max3_f32 v226, v226, v151, v152
	v_max3_f32 v226, v226, v153, v154
	ds_read_b64_tr_b16 v[216:217], v212 offset:1024
	ds_read_b64_tr_b16 v[218:219], v212 offset:5120
	ds_read_b64_tr_b16 v[220:221], v212 offset:9216
	ds_read_b64_tr_b16 v[222:223], v212 offset:13312
	s_waitcnt lgkmcnt(6)
	v_mfma_f32_32x32x16_bf16 v[98:113], v[156:159], v[236:239], v[98:113]
	v_max_f32_e32 v226, v226, v155
	v_mov_b32_e32 v227, v226
	s_nop 1
	v_permlane32_swap_b32_e32 v226, v227
	v_max_f32_e32 v226, v226, v227
	v_fma_f32 v226, v226, s82, v231
	v_sub_f32_e32 v227, v226, v213
	s_mov_b32 s48, 0x4138aa3b
	s_waitcnt lgkmcnt(4)
	v_mfma_f32_32x32x16_bf16 v[98:113], v[160:163], v[240:243], v[98:113]
	v_cmp_ge_f32_e32 vcc, s48, v227
	s_cmp_eq_u64 vcc, exec
	v_max_f32_e32 v226, v213, v226
	s_cselect_b64 vcc, -1, 0
	v_sub_f32_e32 v227, v213, v226
	v_cndmask_b32_e32 v213, v226, v213, vcc
	v_sub_f32_e32 v230, v231, v213
	v_fma_f32 v140, v140, s82, v230
	ds_read_b64_tr_b16 v[236:237], v212 offset:1536
	ds_read_b64_tr_b16 v[238:239], v212 offset:5632
	ds_read_b64_tr_b16 v[240:241], v212 offset:9728
	ds_read_b64_tr_b16 v[242:243], v212 offset:13824
	s_waitcnt lgkmcnt(6)
	v_mfma_f32_32x32x16_bf16 v[82:97], v[156:159], v[216:219], v[82:97]
	v_exp_f32_e32 v140, v140
	v_fma_f32 v141, v141, s82, v230
	v_exp_f32_e32 v141, v141
	v_fma_f32 v142, v142, s82, v230
	v_exp_f32_e32 v142, v142
	s_waitcnt lgkmcnt(4)
	v_mfma_f32_32x32x16_bf16 v[82:97], v[160:163], v[220:223], v[82:97]
	v_add_f32_e32 v226, v140, v141
	v_fma_f32 v143, v143, s82, v230
	v_exp_f32_e32 v143, v143
	v_add_f32_e32 v226, v226, v142
	v_fma_f32 v144, v144, s82, v230
	v_exp_f32_e32 v144, v144
	ds_read_b64_tr_b16 v[216:217], v212 offset:2048
	ds_read_b64_tr_b16 v[218:219], v212 offset:6144
	ds_read_b64_tr_b16 v[220:221], v212 offset:10240
	ds_read_b64_tr_b16 v[222:223], v212 offset:14336
	s_waitcnt lgkmcnt(6)
	v_mfma_f32_32x32x16_bf16 v[66:81], v[156:159], v[236:239], v[66:81]
	v_add_f32_e32 v226, v226, v143
	v_fma_f32 v145, v145, s82, v230
	v_exp_f32_e32 v145, v145
	v_add_f32_e32 v226, v226, v144
	v_fma_f32 v146, v146, s82, v230
	v_exp_f32_e32 v146, v146
	s_waitcnt lgkmcnt(4)
	v_mfma_f32_32x32x16_bf16 v[66:81], v[160:163], v[240:243], v[66:81]
	v_add_f32_e32 v226, v226, v145
	v_fma_f32 v147, v147, s82, v230
	v_exp_f32_e32 v147, v147
	v_add_f32_e32 v226, v226, v146
	v_fma_f32 v148, v148, s82, v230
	v_exp_f32_e32 v148, v148
	ds_read_b64_tr_b16 v[236:237], v212 offset:2560
	ds_read_b64_tr_b16 v[238:239], v212 offset:6656
	ds_read_b64_tr_b16 v[240:241], v212 offset:10752
	ds_read_b64_tr_b16 v[242:243], v212 offset:14848
	s_waitcnt lgkmcnt(6)
	v_mfma_f32_32x32x16_bf16 v[50:65], v[156:159], v[216:219], v[50:65]
	v_add_f32_e32 v226, v226, v147
	v_fma_f32 v149, v149, s82, v230
	v_exp_f32_e32 v149, v149
	v_add_f32_e32 v226, v226, v148
	v_fma_f32 v150, v150, s82, v230
	v_exp_f32_e32 v150, v150
	s_waitcnt lgkmcnt(4)
	v_mfma_f32_32x32x16_bf16 v[50:65], v[160:163], v[220:223], v[50:65]
	v_add_f32_e32 v226, v226, v149
	v_fma_f32 v151, v151, s82, v230
	v_exp_f32_e32 v151, v151
	v_add_f32_e32 v226, v226, v150
	v_fma_f32 v152, v152, s82, v230
	ds_read_b64_tr_b16 v[216:217], v212 offset:3072
	ds_read_b64_tr_b16 v[218:219], v212 offset:7168
	ds_read_b64_tr_b16 v[220:221], v212 offset:11264
	ds_read_b64_tr_b16 v[222:223], v212 offset:15360
	s_waitcnt lgkmcnt(6)
	v_mfma_f32_32x32x16_bf16 v[34:49], v[156:159], v[236:239], v[34:49]
	v_exp_f32_e32 v152, v152
	v_add_f32_e32 v226, v226, v151
	v_fma_f32 v153, v153, s82, v230
	v_exp_f32_e32 v153, v153
	s_waitcnt lgkmcnt(4)
	v_mfma_f32_32x32x16_bf16 v[34:49], v[160:163], v[240:243], v[34:49]
	v_add_f32_e32 v226, v226, v152
	v_fma_f32 v154, v154, s82, v230
	v_exp_f32_e32 v154, v154
	v_add_f32_e32 v226, v226, v153
	v_fma_f32 v155, v155, s82, v230
	ds_read_b64_tr_b16 v[236:237], v212 offset:3584
	ds_read_b64_tr_b16 v[238:239], v212 offset:7680
	ds_read_b64_tr_b16 v[240:241], v212 offset:11776
	ds_read_b64_tr_b16 v[242:243], v212 offset:15872
	s_waitcnt lgkmcnt(6)
	v_mfma_f32_32x32x16_bf16 v[18:33], v[156:159], v[216:219], v[18:33]
	v_exp_f32_e32 v155, v155
	v_add_f32_e32 v226, v226, v154
	v_exp_f32_e32 v227, v227
	v_add_f32_e32 v228, v226, v155
	s_waitcnt lgkmcnt(4)
	v_mfma_f32_32x32x16_bf16 v[18:33], v[160:163], v[220:223], v[18:33]
	v_cndmask_b32_e64 v227, v227, 1.0, vcc
	v_mov_b32_e32 v229, v228
	v_cvt_pk_bf16_f32 v132, v140, v141
	v_cvt_pk_bf16_f32 v133, v142, v143
	v_cvt_pk_bf16_f32 v134, v144, v145
	v_cvt_pk_bf16_f32 v135, v146, v147
	s_waitcnt lgkmcnt(2)
	v_mfma_f32_32x32x16_bf16 v[2:17], v[156:159], v[236:239], v[2:17]
	v_cvt_pk_bf16_f32 v136, v148, v149
	v_cvt_pk_bf16_f32 v137, v150, v151
	v_cvt_pk_bf16_f32 v138, v152, v153
	v_cvt_pk_bf16_f32 v139, v154, v155
	v_permlane32_swap_b32_e32 v228, v229
	v_permlane32_swap_b32_e32 v132, v134
	s_waitcnt lgkmcnt(0)
	v_mfma_f32_32x32x16_bf16 v[2:17], v[160:163], v[240:243], v[2:17]
	v_permlane32_swap_b32_e32 v133, v135
	v_permlane32_swap_b32_e32 v136, v138
	v_permlane32_swap_b32_e32 v137, v139
	v_add_f32_e32 v228, v228, v229
	v_fma_f32 v130, v130, v227, v228
	v_cmp_gt_f32_e32 vcc, 1.0, v227
	s_cbranch_vccz .Lattn_norescale1
; DI int crow(int r, int hi) { return (r & 3) + 8 * (r >> 2) + 4 * hi; }
; DI void phase_attn(int wid0, const Params& p, int L, unsigned char* lds, bool dry) {
;     ...
;                 if (__any(alpha < 1.f)) {
;                     if (hi == 0) al_l[r32] = alpha;
;                     asm volatile("s_waitcnt lgkmcnt(0)" ::: "memory");
;                     float ar[16];
; #pragma unroll
;                     for (int r = 0; r < 16; ++r) ar[r] = al_l[crow(r, hi)];
; #pragma unroll
;                     for (int d = 0; d < 8; ++d)
; #pragma unroll
;                         for (int r = 0; r < 16; ++r) o[d][r] *= ar[r];
;                 }
	s_and_saveexec_b64 s[80:81], s[8:9]
	ds_write_b32 v196, v227 offset:128
	s_or_b64 exec, exec, s[80:81]
	s_waitcnt lgkmcnt(0)
	ds_read_b128 v[152:155], v214 offset:224
	ds_read_b128 v[148:151], v214 offset:192
	ds_read_b128 v[144:147], v214 offset:160
	ds_read_b128 v[140:143], v214 offset:128
	s_waitcnt lgkmcnt(0)
	v_pk_mul_f32 v[126:127], v[126:127], v[152:153]
	v_pk_mul_f32 v[122:123], v[122:123], v[148:149]
	v_pk_mul_f32 v[118:119], v[118:119], v[144:145]
	v_pk_mul_f32 v[128:129], v[128:129], v[154:155]
	v_pk_mul_f32 v[124:125], v[124:125], v[150:151]
	v_pk_mul_f32 v[120:121], v[120:121], v[146:147]
	v_pk_mul_f32 v[116:117], v[116:117], v[142:143]
	v_pk_mul_f32 v[114:115], v[114:115], v[140:141]
	v_pk_mul_f32 v[110:111], v[110:111], v[152:153]
	v_pk_mul_f32 v[106:107], v[106:107], v[148:149]
	v_pk_mul_f32 v[102:103], v[102:103], v[144:145]
	v_pk_mul_f32 v[112:113], v[112:113], v[154:155]
	v_pk_mul_f32 v[108:109], v[108:109], v[150:151]
	v_pk_mul_f32 v[104:105], v[104:105], v[146:147]
	v_pk_mul_f32 v[100:101], v[100:101], v[142:143]
	v_pk_mul_f32 v[98:99], v[98:99], v[140:141]
	v_pk_mul_f32 v[94:95], v[94:95], v[152:153]
	v_pk_mul_f32 v[90:91], v[90:91], v[148:149]
	v_pk_mul_f32 v[86:87], v[86:87], v[144:145]
	v_pk_mul_f32 v[96:97], v[96:97], v[154:155]
	v_pk_mul_f32 v[92:93], v[92:93], v[150:151]
	v_pk_mul_f32 v[88:89], v[88:89], v[146:147]
	v_pk_mul_f32 v[84:85], v[84:85], v[142:143]
	v_pk_mul_f32 v[82:83], v[82:83], v[140:141]
	v_pk_mul_f32 v[78:79], v[78:79], v[152:153]
	v_pk_mul_f32 v[74:75], v[74:75], v[148:149]
	v_pk_mul_f32 v[70:71], v[70:71], v[144:145]
	v_pk_mul_f32 v[80:81], v[80:81], v[154:155]
	v_pk_mul_f32 v[76:77], v[76:77], v[150:151]
	v_pk_mul_f32 v[72:73], v[72:73], v[146:147]
	v_pk_mul_f32 v[68:69], v[68:69], v[142:143]
	v_pk_mul_f32 v[66:67], v[66:67], v[140:141]
	v_pk_mul_f32 v[62:63], v[62:63], v[152:153]
	v_pk_mul_f32 v[58:59], v[58:59], v[148:149]
	v_pk_mul_f32 v[54:55], v[54:55], v[144:145]
	v_pk_mul_f32 v[64:65], v[64:65], v[154:155]
	v_pk_mul_f32 v[60:61], v[60:61], v[150:151]
	v_pk_mul_f32 v[56:57], v[56:57], v[146:147]
	v_pk_mul_f32 v[52:53], v[52:53], v[142:143]
	v_pk_mul_f32 v[50:51], v[50:51], v[140:141]
	v_pk_mul_f32 v[46:47], v[46:47], v[152:153]
	v_pk_mul_f32 v[42:43], v[42:43], v[148:149]
	v_pk_mul_f32 v[38:39], v[38:39], v[144:145]
	v_pk_mul_f32 v[48:49], v[48:49], v[154:155]
	v_pk_mul_f32 v[44:45], v[44:45], v[150:151]
	v_pk_mul_f32 v[40:41], v[40:41], v[146:147]
	v_pk_mul_f32 v[36:37], v[36:37], v[142:143]
	v_pk_mul_f32 v[34:35], v[34:35], v[140:141]
	v_pk_mul_f32 v[30:31], v[30:31], v[152:153]
	v_pk_mul_f32 v[26:27], v[26:27], v[148:149]
	v_pk_mul_f32 v[22:23], v[22:23], v[144:145]
	v_pk_mul_f32 v[32:33], v[32:33], v[154:155]
	v_pk_mul_f32 v[28:29], v[28:29], v[150:151]
	v_pk_mul_f32 v[24:25], v[24:25], v[146:147]
	v_pk_mul_f32 v[20:21], v[20:21], v[142:143]
	v_pk_mul_f32 v[18:19], v[18:19], v[140:141]
	v_pk_mul_f32 v[14:15], v[14:15], v[152:153]
	v_pk_mul_f32 v[10:11], v[10:11], v[148:149]
	v_pk_mul_f32 v[6:7], v[6:7], v[144:145]
	v_pk_mul_f32 v[16:17], v[16:17], v[154:155]
	v_pk_mul_f32 v[12:13], v[12:13], v[150:151]
	v_pk_mul_f32 v[8:9], v[8:9], v[146:147]
	v_pk_mul_f32 v[4:5], v[4:5], v[142:143]
	v_pk_mul_f32 v[2:3], v[2:3], v[140:141]

; #define LAS __attribute__((address_space(3)))
; DI int v_rd_base(int lane) { return ((lane & 3) << 3) | (((lane >> 2) & 3) << 6) | (((lane >> 4) & 1) << 5) | (((lane >> 5) & 1) << 8); }
; #define PV_RD(D0, L0, H0, L1, H1) L0 = TRB(v_rd_off(D0, 0, 0)); H0 = TRB(v_rd_off(D0, 0, 1)); L1 = TRB(v_rd_off(D0, 1, 0)); H1 = TRB(v_rd_off(D0, 1, 1))
; #define PV_MM(D0, L0, H0, L1, H1) o[D0] = MFMA32(pa0, PK8(L0, H0), o[D0]); o[D0] = MFMA32(pa1, PK8(L1, H1), o[D0])
; #define SB() __builtin_amdgcn_sched_barrier(0)
; DI void phase_attn(int wid0, const Params& p, int L, unsigned char* lds, bool dry) {
;     ...
;                 LAS unsigned char* vbp = ldsl + 65536 + (t & 1) * 32768 + 16384 + v_rd_base(lane);
;                 __builtin_amdgcn_s_setprio(1);
;     ...
;                 {
;                     s16x4 a0, a1, a2, a3, b0_, b1_, b2_, b3_;
;                     PV_RD(0, a0, a1, a2, a3); SB();
;                     PV_RD(1, b0_, b1_, b2_, b3_); SB(); PV_MM(0, a0, a1, a2, a3); SB();
;                     PV_RD(2, a0, a1, a2, a3); SB(); PV_MM(1, b0_, b1_, b2_, b3_); SB();
;                     PV_RD(3, b0_, b1_, b2_, b3_); SB(); PV_MM(2, a0, a1, a2, a3); SB();
;                     PV_RD(4, a0, a1, a2, a3); SB(); PV_MM(3, b0_, b1_, b2_, b3_); SB();
;                     PV_RD(5, b0_, b1_, b2_, b3_); SB(); PV_MM(4, a0, a1, a2, a3); SB();
;                     PV_RD(6, a0, a1, a2, a3); SB(); PV_MM(5, b0_, b1_, b2_, b3_); SB();
;                     PV_RD(7, b0_, b1_, b2_, b3_); SB(); PV_MM(6, a0, a1, a2, a3); SB();
;                     PV_MM(7, b0_, b1_, b2_, b3_); SB();
;                 }
;     ...
;                 __builtin_amdgcn_s_setprio(0);
.Lattn_pvplain0:
	s_setprio 1
	ds_read_b64_tr_b16 v[140:141], v212 offset:0
	ds_read_b64_tr_b16 v[142:143], v212 offset:4096
	ds_read_b64_tr_b16 v[144:145], v212 offset:8192
	ds_read_b64_tr_b16 v[146:147], v212 offset:12288
	ds_read_b64_tr_b16 v[148:149], v212 offset:512
	ds_read_b64_tr_b16 v[150:151], v212 offset:4608
	ds_read_b64_tr_b16 v[152:153], v212 offset:8704
	ds_read_b64_tr_b16 v[154:155], v212 offset:12800
	s_waitcnt lgkmcnt(6)
	v_mfma_f32_32x32x16_bf16 v[114:129], v[156:159], v[140:143], v[114:129]
	s_waitcnt lgkmcnt(4)
	v_mfma_f32_32x32x16_bf16 v[114:129], v[160:163], v[144:147], v[114:129]
	ds_read_b64_tr_b16 v[140:141], v212 offset:1024
	ds_read_b64_tr_b16 v[142:143], v212 offset:5120
	ds_read_b64_tr_b16 v[144:145], v212 offset:9216
	ds_read_b64_tr_b16 v[146:147], v212 offset:13312
	s_waitcnt lgkmcnt(6)
	v_mfma_f32_32x32x16_bf16 v[98:113], v[156:159], v[148:151], v[98:113]
	s_waitcnt lgkmcnt(4)
	v_mfma_f32_32x32x16_bf16 v[98:113], v[160:163], v[152:155], v[98:113]
	ds_read_b64_tr_b16 v[148:149], v212 offset:1536
	ds_read_b64_tr_b16 v[150:151], v212 offset:5632
	ds_read_b64_tr_b16 v[152:153], v212 offset:9728
	ds_read_b64_tr_b16 v[154:155], v212 offset:13824
	s_waitcnt lgkmcnt(6)
	v_mfma_f32_32x32x16_bf16 v[82:97], v[156:159], v[140:143], v[82:97]
	s_waitcnt lgkmcnt(4)
	v_mfma_f32_32x32x16_bf16 v[82:97], v[160:163], v[144:147], v[82:97]
	ds_read_b64_tr_b16 v[140:141], v212 offset:2048
	ds_read_b64_tr_b16 v[142:143], v212 offset:6144
	ds_read_b64_tr_b16 v[144:145], v212 offset:10240
	ds_read_b64_tr_b16 v[146:147], v212 offset:14336
	s_waitcnt lgkmcnt(6)
	v_mfma_f32_32x32x16_bf16 v[66:81], v[156:159], v[148:151], v[66:81]
	s_waitcnt lgkmcnt(4)
	v_mfma_f32_32x32x16_bf16 v[66:81], v[160:163], v[152:155], v[66:81]
	ds_read_b64_tr_b16 v[148:149], v212 offset:2560
	ds_read_b64_tr_b16 v[150:151], v212 offset:6656
	ds_read_b64_tr_b16 v[152:153], v212 offset:10752
	ds_read_b64_tr_b16 v[154:155], v212 offset:14848
	s_waitcnt lgkmcnt(6)
	v_mfma_f32_32x32x16_bf16 v[50:65], v[156:159], v[140:143], v[50:65]
	s_waitcnt lgkmcnt(4)
	v_mfma_f32_32x32x16_bf16 v[50:65], v[160:163], v[144:147], v[50:65]
	ds_read_b64_tr_b16 v[140:141], v212 offset:3072
	ds_read_b64_tr_b16 v[142:143], v212 offset:7168
	ds_read_b64_tr_b16 v[144:145], v212 offset:11264
	ds_read_b64_tr_b16 v[146:147], v212 offset:15360
	s_waitcnt lgkmcnt(6)
	v_mfma_f32_32x32x16_bf16 v[34:49], v[156:159], v[148:151], v[34:49]
	s_waitcnt lgkmcnt(4)
	v_mfma_f32_32x32x16_bf16 v[34:49], v[160:163], v[152:155], v[34:49]
	ds_read_b64_tr_b16 v[148:149], v212 offset:3584
	ds_read_b64_tr_b16 v[150:151], v212 offset:7680
	ds_read_b64_tr_b16 v[152:153], v212 offset:11776
	ds_read_b64_tr_b16 v[154:155], v212 offset:15872
	s_waitcnt lgkmcnt(6)
	v_mfma_f32_32x32x16_bf16 v[18:33], v[156:159], v[140:143], v[18:33]
	s_waitcnt lgkmcnt(4)
	v_mfma_f32_32x32x16_bf16 v[18:33], v[160:163], v[144:147], v[18:33]
	s_waitcnt lgkmcnt(2)
	v_mfma_f32_32x32x16_bf16 v[2:17], v[156:159], v[148:151], v[2:17]
	s_waitcnt lgkmcnt(0)
	v_mfma_f32_32x32x16_bf16 v[2:17], v[160:163], v[152:155], v[2:17]
	s_setprio 0
	s_andn2_b32 s100, s100, 0x100
	s_bitcmp1_b32 s100, 9
	s_cbranch_scc1 .LBB0_113

; #define LAS __attribute__((address_space(3)))
; DI void attn_stage(const bf16_t* kbase, const bf16_t* vbase, unsigned koff, unsigned voff, LAS unsigned char* ldsbuf, int wid) {
; #pragma unroll
;     for (int i = 0; i < 2; ++i) {
;         const char* src = (const char*)kbase + (size_t)(i * 128) * 2;
;         __builtin_amdgcn_global_load_lds((const unsigned*)(src + koff), (LAS unsigned*)(ldsbuf + (wid + 8 * i) * 1024), 16, 0, 0);
;     }
; #pragma unroll
;     for (int i = 0; i < 2; ++i) {
;         const char* src = (const char*)vbase + (size_t)(16 * i * 2048) * 2;
;         __builtin_amdgcn_global_load_lds((const unsigned*)(src + voff), (LAS unsigned*)(ldsbuf + 16384 + (wid + 8 * i) * 1024), 16, 0, 0);
;     }
; }
; DI void phase_attn(int wid0, const Params& p, int L, unsigned char* lds, bool dry) {
;     ...
;             asm volatile("s_waitcnt vmcnt(0) lgkmcnt(0)" ::: "memory"); __builtin_amdgcn_s_barrier(); asm volatile("" ::: "memory");
;             if (t + 1 < ntiles) attn_stage(kh_ + (size_t)(b * 4096 + 32 * t) * 2048, vh_ + (size_t)(b * 4096 + 32 * t) * 2048, koff, voff, ldsl + 65536 + ((t + 1) & 1) * 32768, wid);
;             const int kpos0 = (t == 0) ? 0 : 16 + 32 * (t - 1);
.Lattn_top2:
	s_waitcnt vmcnt(0) lgkmcnt(0)
	s_barrier
	s_add_i32 s67, s69, 1
	s_cmp_ge_i32 s67, s6
	s_cbranch_scc1 .Lattn_nodma2
	s_add_i32 m0, s4, 0x8000
	s_nop 0
	global_load_lds_dwordx4 v131, s[88:89]
	s_add_i32 m0, s4, 0xa000
	s_nop 0
	global_load_lds_dwordx4 v131, s[90:91]
	s_add_i32 m0, s96, 0xc000
	s_add_u32 s88, s88, 0x20000
	global_load_lds_dwordx4 v208, s[92:93]
	s_addc_u32 s89, s89, 0
	s_add_i32 m0, s96, 0xe000
	s_add_u32 s92, s92, 0x20000
	global_load_lds_dwordx4 v208, s[94:95]
	s_addc_u32 s93, s93, 0
	s_add_u32 s94, s94, 0x20000
	s_addc_u32 s95, s95, 0
	s_add_u32 s90, s90, 0x20000
	s_addc_u32 s91, s91, 0

; DI void phase_attn(int wid0, const Params& p, int L, unsigned char* lds, bool dry) {
;     ...
;                 float pmax = p0[0];
; #pragma unroll
;                 for (int r = 1; r < 16; ++r) pmax = fmaxf(pmax, p0[r]);
;                 { auto rr = __builtin_amdgcn_permlane32_swap(__float_as_uint(pmax), __float_as_uint(pmax), false, false); pmax = fmaxf(__uint_as_float(rr[0]), __uint_as_float(rr[1])); }
;                 float mn, alpha;
;                 if (__all(pmax - m_reg <= ATT_THR2)) { mn = m_reg; alpha = 1.f; }
;                 else { mn = fmaxf(m_reg, pmax); alpha = __builtin_amdgcn_exp2f(m_reg - mn); m_reg = mn; }
;                 float ps = 0.f;
; #pragma unroll
;                 for (int r = 0; r < 16; ++r) { p0[r] = __builtin_amdgcn_exp2f(p0[r] - mn); ps += p0[r]; }
;                 { auto rr = __builtin_amdgcn_permlane32_swap(__float_as_uint(ps), __float_as_uint(ps), false, false); ps = __uint_as_float(rr[0]) + __uint_as_float(rr[1]); }
;                 l_reg = l_reg * alpha + ps;
;                 __builtin_amdgcn_sched_barrier(0);
;                 bf16x8 pa0, pa1;
;     ...
;                 PK4(p0, 0, pa0); PK4(p0, 8, pa1);
;     ...
;                 __builtin_amdgcn_sched_barrier(0);
;                 if (__any(alpha < 1.f)) {
;                     if (hi == 0) al_l[r32] = alpha;
;                     asm volatile("s_waitcnt lgkmcnt(0)" ::: "memory");
;                     float ar[16];
; #pragma unroll
;                     for (int r = 0; r < 16; ++r) ar[r] = al_l[crow(r, hi)];
; #pragma unroll
;                     for (int d = 0; d < 8; ++d)
; #pragma unroll
;                         for (int r = 0; r < 16; ++r) o[d][r] *= ar[r];
;                 }
;                 __builtin_amdgcn_sched_barrier(0);
;                 LAS unsigned char* vbp = ldsl + 65536 + (t & 1) * 32768 + 16384 + v_rd_base(lane);
;                 __builtin_amdgcn_s_setprio(1);
;     ...
;                 {
;                     s16x4 a0, a1, a2, a3, b0_, b1_, b2_, b3_;
;                     PV_RD(0, a0, a1, a2, a3); SB();
;                     PV_RD(1, b0_, b1_, b2_, b3_); SB(); PV_MM(0, a0, a1, a2, a3); SB();
;                     PV_RD(2, a0, a1, a2, a3); SB(); PV_MM(1, b0_, b1_, b2_, b3_); SB();
;                     PV_RD(3, b0_, b1_, b2_, b3_); SB(); PV_MM(2, a0, a1, a2, a3); SB();
;                     PV_RD(4, a0, a1, a2, a3); SB(); PV_MM(3, b0_, b1_, b2_, b3_); SB();
.Lattn_region2:
	ds_read_b64_tr_b16 v[216:217], v212 offset:16384
	ds_read_b64_tr_b16 v[218:219], v212 offset:20480
	ds_read_b64_tr_b16 v[220:221], v212 offset:24576
	ds_read_b64_tr_b16 v[222:223], v212 offset:28672
	ds_read_b64_tr_b16 v[236:237], v212 offset:16896
	ds_read_b64_tr_b16 v[238:239], v212 offset:20992
	ds_read_b64_tr_b16 v[240:241], v212 offset:25088
	ds_read_b64_tr_b16 v[242:243], v212 offset:29184
	s_waitcnt lgkmcnt(6)
	v_mfma_f32_32x32x16_bf16 v[114:129], v[132:135], v[216:219], v[114:129]
	s_waitcnt lgkmcnt(4)
	v_mfma_f32_32x32x16_bf16 v[114:129], v[136:139], v[220:223], v[114:129]
	v_max3_f32 v226, v140, v141, v142
	v_max3_f32 v226, v226, v143, v144
	v_max3_f32 v226, v226, v145, v146
	v_max3_f32 v226, v226, v147, v148
	v_max3_f32 v226, v226, v149, v150
	v_max3_f32 v226, v226, v151, v152
	v_max3_f32 v226, v226, v153, v154
	ds_read_b64_tr_b16 v[216:217], v212 offset:17408
	ds_read_b64_tr_b16 v[218:219], v212 offset:21504
	ds_read_b64_tr_b16 v[220:221], v212 offset:25600
	ds_read_b64_tr_b16 v[222:223], v212 offset:29696
	s_waitcnt lgkmcnt(6)
	v_mfma_f32_32x32x16_bf16 v[98:113], v[132:135], v[236:239], v[98:113]
	v_max_f32_e32 v226, v226, v155
	v_mov_b32_e32 v227, v226
	s_nop 1
	v_permlane32_swap_b32_e32 v226, v227
	v_max_f32_e32 v226, v226, v227
	v_fma_f32 v226, v226, s82, v231
	v_sub_f32_e32 v227, v226, v213
	s_mov_b32 s48, 0x4138aa3b
	s_waitcnt lgkmcnt(4)
	v_mfma_f32_32x32x16_bf16 v[98:113], v[136:139], v[240:243], v[98:113]
	v_cmp_ge_f32_e32 vcc, s48, v227
	s_cmp_eq_u64 vcc, exec
	v_max_f32_e32 v226, v213, v226
	s_cselect_b64 vcc, -1, 0
	v_sub_f32_e32 v227, v213, v226
	v_cndmask_b32_e32 v213, v226, v213, vcc
	v_sub_f32_e32 v230, v231, v213
	v_fma_f32 v140, v140, s82, v230
	ds_read_b64_tr_b16 v[236:237], v212 offset:17920
	ds_read_b64_tr_b16 v[238:239], v212 offset:22016
	ds_read_b64_tr_b16 v[240:241], v212 offset:26112
	ds_read_b64_tr_b16 v[242:243], v212 offset:30208
	s_waitcnt lgkmcnt(6)
	v_mfma_f32_32x32x16_bf16 v[82:97], v[132:135], v[216:219], v[82:97]
	v_exp_f32_e32 v140, v140
	v_fma_f32 v141, v141, s82, v230
	v_exp_f32_e32 v141, v141
	v_fma_f32 v142, v142, s82, v230
	v_exp_f32_e32 v142, v142
	s_waitcnt lgkmcnt(4)
	v_mfma_f32_32x32x16_bf16 v[82:97], v[136:139], v[220:223], v[82:97]
	v_add_f32_e32 v226, v140, v141
	v_fma_f32 v143, v143, s82, v230
	v_exp_f32_e32 v143, v143
	v_add_f32_e32 v226, v226, v142
	v_fma_f32 v144, v144, s82, v230
	v_exp_f32_e32 v144, v144
	ds_read_b64_tr_b16 v[216:217], v212 offset:18432
	ds_read_b64_tr_b16 v[218:219], v212 offset:22528
	ds_read_b64_tr_b16 v[220:221], v212 offset:26624
	ds_read_b64_tr_b16 v[222:223], v212 offset:30720
	s_waitcnt lgkmcnt(6)
	v_mfma_f32_32x32x16_bf16 v[66:81], v[132:135], v[236:239], v[66:81]
	v_add_f32_e32 v226, v226, v143
	v_fma_f32 v145, v145, s82, v230
	v_exp_f32_e32 v145, v145
	v_add_f32_e32 v226, v226, v144
	v_fma_f32 v146, v146, s82, v230
	v_exp_f32_e32 v146, v146
	s_waitcnt lgkmcnt(4)
	v_mfma_f32_32x32x16_bf16 v[66:81], v[136:139], v[240:243], v[66:81]
	v_add_f32_e32 v226, v226, v145
	v_fma_f32 v147, v147, s82, v230
	v_exp_f32_e32 v147, v147
	v_add_f32_e32 v226, v226, v146
	v_fma_f32 v148, v148, s82, v230
	v_exp_f32_e32 v148, v148
	ds_read_b64_tr_b16 v[236:237], v212 offset:18944
	ds_read_b64_tr_b16 v[238:239], v212 offset:23040
	ds_read_b64_tr_b16 v[240:241], v212 offset:27136
	ds_read_b64_tr_b16 v[242:243], v212 offset:31232
	s_waitcnt lgkmcnt(6)
	v_mfma_f32_32x32x16_bf16 v[50:65], v[132:135], v[216:219], v[50:65]
	v_add_f32_e32 v226, v226, v147
	v_fma_f32 v149, v149, s82, v230
	v_exp_f32_e32 v149, v149
	v_add_f32_e32 v226, v226, v148
	v_fma_f32 v150, v150, s82, v230
	v_exp_f32_e32 v150, v150
	s_waitcnt lgkmcnt(4)
	v_mfma_f32_32x32x16_bf16 v[50:65], v[136:139], v[220:223], v[50:65]
	v_add_f32_e32 v226, v226, v149
	v_fma_f32 v151, v151, s82, v230
	v_exp_f32_e32 v151, v151
	v_add_f32_e32 v226, v226, v150
	v_fma_f32 v152, v152, s82, v230
	ds_read_b64_tr_b16 v[216:217], v212 offset:19456
	ds_read_b64_tr_b16 v[218:219], v212 offset:23552
	ds_read_b64_tr_b16 v[220:221], v212 offset:27648
	ds_read_b64_tr_b16 v[222:223], v212 offset:31744
	s_waitcnt lgkmcnt(6)
	v_mfma_f32_32x32x16_bf16 v[34:49], v[132:135], v[236:239], v[34:49]
	v_exp_f32_e32 v152, v152
	v_add_f32_e32 v226, v226, v151
	v_fma_f32 v153, v153, s82, v230
	v_exp_f32_e32 v153, v153
	s_waitcnt lgkmcnt(4)
	v_mfma_f32_32x32x16_bf16 v[34:49], v[136:139], v[240:243], v[34:49]
	v_add_f32_e32 v226, v226, v152
	v_fma_f32 v154, v154, s82, v230
	v_exp_f32_e32 v154, v154
	v_add_f32_e32 v226, v226, v153
	v_fma_f32 v155, v155, s82, v230
	ds_read_b64_tr_b16 v[236:237], v212 offset:19968
	ds_read_b64_tr_b16 v[238:239], v212 offset:24064
	ds_read_b64_tr_b16 v[240:241], v212 offset:28160
	ds_read_b64_tr_b16 v[242:243], v212 offset:32256
	s_waitcnt lgkmcnt(6)
	v_mfma_f32_32x32x16_bf16 v[18:33], v[132:135], v[216:219], v[18:33]
	v_exp_f32_e32 v155, v155
	v_add_f32_e32 v226, v226, v154
	v_exp_f32_e32 v227, v227
	v_add_f32_e32 v228, v226, v155
	s_waitcnt lgkmcnt(4)
	v_mfma_f32_32x32x16_bf16 v[18:33], v[136:139], v[220:223], v[18:33]
	v_cndmask_b32_e64 v227, v227, 1.0, vcc
	v_mov_b32_e32 v229, v228
	v_cvt_pk_bf16_f32 v156, v140, v141
	v_cvt_pk_bf16_f32 v157, v142, v143
	v_cvt_pk_bf16_f32 v158, v144, v145
	v_cvt_pk_bf16_f32 v159, v146, v147
	s_waitcnt lgkmcnt(2)
	v_mfma_f32_32x32x16_bf16 v[2:17], v[132:135], v[236:239], v[2:17]
	v_cvt_pk_bf16_f32 v160, v148, v149
	v_cvt_pk_bf16_f32 v161, v150, v151
	v_cvt_pk_bf16_f32 v162, v152, v153
	v_cvt_pk_bf16_f32 v163, v154, v155
	v_permlane32_swap_b32_e32 v228, v229
	v_permlane32_swap_b32_e32 v156, v158
	s_waitcnt lgkmcnt(0)
	v_mfma_f32_32x32x16_bf16 v[2:17], v[136:139], v[240:243], v[2:17]
	v_permlane32_swap_b32_e32 v157, v159
	v_permlane32_swap_b32_e32 v160, v162
	v_permlane32_swap_b32_e32 v161, v163
	v_add_f32_e32 v228, v228, v229
	v_fma_f32 v130, v130, v227, v228
	v_cmp_gt_f32_e32 vcc, 1.0, v227
	s_cbranch_vccz .Lattn_norescale2
; DI int crow(int r, int hi) { return (r & 3) + 8 * (r >> 2) + 4 * hi; }
; DI void phase_attn(int wid0, const Params& p, int L, unsigned char* lds, bool dry) {
;     ...
;                 if (__any(alpha < 1.f)) {
;                     if (hi == 0) al_l[r32] = alpha;
;                     asm volatile("s_waitcnt lgkmcnt(0)" ::: "memory");
;                     float ar[16];
; #pragma unroll
;                     for (int r = 0; r < 16; ++r) ar[r] = al_l[crow(r, hi)];
; #pragma unroll
;                     for (int d = 0; d < 8; ++d)
; #pragma unroll
;                         for (int r = 0; r < 16; ++r) o[d][r] *= ar[r];
;                 }
	s_and_saveexec_b64 s[80:81], s[8:9]
	ds_write_b32 v196, v227 offset:128
	s_or_b64 exec, exec, s[80:81]
	s_waitcnt lgkmcnt(0)
	ds_read_b128 v[152:155], v214 offset:224
	ds_read_b128 v[148:151], v214 offset:192
	ds_read_b128 v[144:147], v214 offset:160
	ds_read_b128 v[140:143], v214 offset:128
	s_waitcnt lgkmcnt(0)
	v_pk_mul_f32 v[126:127], v[126:127], v[152:153]
	v_pk_mul_f32 v[122:123], v[122:123], v[148:149]
	v_pk_mul_f32 v[118:119], v[118:119], v[144:145]
	v_pk_mul_f32 v[128:129], v[128:129], v[154:155]
	v_pk_mul_f32 v[124:125], v[124:125], v[150:151]
	v_pk_mul_f32 v[120:121], v[120:121], v[146:147]
	v_pk_mul_f32 v[116:117], v[116:117], v[142:143]
	v_pk_mul_f32 v[114:115], v[114:115], v[140:141]
	v_pk_mul_f32 v[110:111], v[110:111], v[152:153]
	v_pk_mul_f32 v[106:107], v[106:107], v[148:149]
	v_pk_mul_f32 v[102:103], v[102:103], v[144:145]
	v_pk_mul_f32 v[112:113], v[112:113], v[154:155]
	v_pk_mul_f32 v[108:109], v[108:109], v[150:151]
	v_pk_mul_f32 v[104:105], v[104:105], v[146:147]
	v_pk_mul_f32 v[100:101], v[100:101], v[142:143]
	v_pk_mul_f32 v[98:99], v[98:99], v[140:141]
	v_pk_mul_f32 v[94:95], v[94:95], v[152:153]
	v_pk_mul_f32 v[90:91], v[90:91], v[148:149]
	v_pk_mul_f32 v[86:87], v[86:87], v[144:145]
	v_pk_mul_f32 v[96:97], v[96:97], v[154:155]
	v_pk_mul_f32 v[92:93], v[92:93], v[150:151]
	v_pk_mul_f32 v[88:89], v[88:89], v[146:147]
	v_pk_mul_f32 v[84:85], v[84:85], v[142:143]
	v_pk_mul_f32 v[82:83], v[82:83], v[140:141]
	v_pk_mul_f32 v[78:79], v[78:79], v[152:153]
	v_pk_mul_f32 v[74:75], v[74:75], v[148:149]
	v_pk_mul_f32 v[70:71], v[70:71], v[144:145]
	v_pk_mul_f32 v[80:81], v[80:81], v[154:155]
	v_pk_mul_f32 v[76:77], v[76:77], v[150:151]
	v_pk_mul_f32 v[72:73], v[72:73], v[146:147]
	v_pk_mul_f32 v[68:69], v[68:69], v[142:143]
	v_pk_mul_f32 v[66:67], v[66:67], v[140:141]
	v_pk_mul_f32 v[62:63], v[62:63], v[152:153]
	v_pk_mul_f32 v[58:59], v[58:59], v[148:149]
	v_pk_mul_f32 v[54:55], v[54:55], v[144:145]
	v_pk_mul_f32 v[64:65], v[64:65], v[154:155]
	v_pk_mul_f32 v[60:61], v[60:61], v[150:151]
	v_pk_mul_f32 v[56:57], v[56:57], v[146:147]
	v_pk_mul_f32 v[52:53], v[52:53], v[142:143]
	v_pk_mul_f32 v[50:51], v[50:51], v[140:141]
	v_pk_mul_f32 v[46:47], v[46:47], v[152:153]
	v_pk_mul_f32 v[42:43], v[42:43], v[148:149]
	v_pk_mul_f32 v[38:39], v[38:39], v[144:145]
	v_pk_mul_f32 v[48:49], v[48:49], v[154:155]
	v_pk_mul_f32 v[44:45], v[44:45], v[150:151]
	v_pk_mul_f32 v[40:41], v[40:41], v[146:147]
	v_pk_mul_f32 v[36:37], v[36:37], v[142:143]
	v_pk_mul_f32 v[34:35], v[34:35], v[140:141]
	v_pk_mul_f32 v[30:31], v[30:31], v[152:153]
	v_pk_mul_f32 v[26:27], v[26:27], v[148:149]
	v_pk_mul_f32 v[22:23], v[22:23], v[144:145]
	v_pk_mul_f32 v[32:33], v[32:33], v[154:155]
	v_pk_mul_f32 v[28:29], v[28:29], v[150:151]
	v_pk_mul_f32 v[24:25], v[24:25], v[146:147]
	v_pk_mul_f32 v[20:21], v[20:21], v[142:143]
	v_pk_mul_f32 v[18:19], v[18:19], v[140:141]
	v_pk_mul_f32 v[14:15], v[14:15], v[152:153]
	v_pk_mul_f32 v[10:11], v[10:11], v[148:149]
	v_pk_mul_f32 v[6:7], v[6:7], v[144:145]
	v_pk_mul_f32 v[16:17], v[16:17], v[154:155]
	v_pk_mul_f32 v[12:13], v[12:13], v[150:151]
	v_pk_mul_f32 v[8:9], v[8:9], v[146:147]
	v_pk_mul_f32 v[4:5], v[4:5], v[142:143]
	v_pk_mul_f32 v[2:3], v[2:3], v[140:141]

; #define LAS __attribute__((address_space(3)))
; DI int v_rd_base(int lane) { return ((lane & 3) << 3) | (((lane >> 2) & 3) << 6) | (((lane >> 4) & 1) << 5) | (((lane >> 5) & 1) << 8); }
; #define PV_RD(D0, L0, H0, L1, H1) L0 = TRB(v_rd_off(D0, 0, 0)); H0 = TRB(v_rd_off(D0, 0, 1)); L1 = TRB(v_rd_off(D0, 1, 0)); H1 = TRB(v_rd_off(D0, 1, 1))
; #define PV_MM(D0, L0, H0, L1, H1) o[D0] = MFMA32(pa0, PK8(L0, H0), o[D0]); o[D0] = MFMA32(pa1, PK8(L1, H1), o[D0])
; #define SB() __builtin_amdgcn_sched_barrier(0)
; DI void phase_attn(int wid0, const Params& p, int L, unsigned char* lds, bool dry) {
;     ...
;                 LAS unsigned char* vbp = ldsl + 65536 + (t & 1) * 32768 + 16384 + v_rd_base(lane);
;                 __builtin_amdgcn_s_setprio(1);
;     ...
;                 {
;                     s16x4 a0, a1, a2, a3, b0_, b1_, b2_, b3_;
;                     PV_RD(0, a0, a1, a2, a3); SB();
;                     PV_RD(1, b0_, b1_, b2_, b3_); SB(); PV_MM(0, a0, a1, a2, a3); SB();
;                     PV_RD(2, a0, a1, a2, a3); SB(); PV_MM(1, b0_, b1_, b2_, b3_); SB();
;                     PV_RD(3, b0_, b1_, b2_, b3_); SB(); PV_MM(2, a0, a1, a2, a3); SB();
;                     PV_RD(4, a0, a1, a2, a3); SB(); PV_MM(3, b0_, b1_, b2_, b3_); SB();
;                     PV_RD(5, b0_, b1_, b2_, b3_); SB(); PV_MM(4, a0, a1, a2, a3); SB();
;                     PV_RD(6, a0, a1, a2, a3); SB(); PV_MM(5, b0_, b1_, b2_, b3_); SB();
;                     PV_RD(7, b0_, b1_, b2_, b3_); SB(); PV_MM(6, a0, a1, a2, a3); SB();
;                     PV_MM(7, b0_, b1_, b2_, b3_); SB();
;                 }
;     ...
;                 __builtin_amdgcn_s_setprio(0);
.Lattn_pvplain1:
	s_setprio 1
	ds_read_b64_tr_b16 v[140:141], v212 offset:16384
	ds_read_b64_tr_b16 v[142:143], v212 offset:20480
	ds_read_b64_tr_b16 v[144:145], v212 offset:24576
	ds_read_b64_tr_b16 v[146:147], v212 offset:28672
	ds_read_b64_tr_b16 v[148:149], v212 offset:16896
	ds_read_b64_tr_b16 v[150:151], v212 offset:20992
	ds_read_b64_tr_b16 v[152:153], v212 offset:25088
	ds_read_b64_tr_b16 v[154:155], v212 offset:29184
	s_waitcnt lgkmcnt(6)
	v_mfma_f32_32x32x16_bf16 v[114:129], v[132:135], v[140:143], v[114:129]
	s_waitcnt lgkmcnt(4)
	v_mfma_f32_32x32x16_bf16 v[114:129], v[136:139], v[144:147], v[114:129]
	ds_read_b64_tr_b16 v[140:141], v212 offset:17408
	ds_read_b64_tr_b16 v[142:143], v212 offset:21504
	ds_read_b64_tr_b16 v[144:145], v212 offset:25600
	ds_read_b64_tr_b16 v[146:147], v212 offset:29696
	s_waitcnt lgkmcnt(6)
	v_mfma_f32_32x32x16_bf16 v[98:113], v[132:135], v[148:151], v[98:113]
	s_waitcnt lgkmcnt(4)
	v_mfma_f32_32x32x16_bf16 v[98:113], v[136:139], v[152:155], v[98:113]
	ds_read_b64_tr_b16 v[148:149], v212 offset:17920
	ds_read_b64_tr_b16 v[150:151], v212 offset:22016
	ds_read_b64_tr_b16 v[152:153], v212 offset:26112
	ds_read_b64_tr_b16 v[154:155], v212 offset:30208
	s_waitcnt lgkmcnt(6)
	v_mfma_f32_32x32x16_bf16 v[82:97], v[132:135], v[140:143], v[82:97]
	s_waitcnt lgkmcnt(4)
	v_mfma_f32_32x32x16_bf16 v[82:97], v[136:139], v[144:147], v[82:97]
	ds_read_b64_tr_b16 v[140:141], v212 offset:18432
	ds_read_b64_tr_b16 v[142:143], v212 offset:22528
	ds_read_b64_tr_b16 v[144:145], v212 offset:26624
	ds_read_b64_tr_b16 v[146:147], v212 offset:30720
	s_waitcnt lgkmcnt(6)
	v_mfma_f32_32x32x16_bf16 v[66:81], v[132:135], v[148:151], v[66:81]
	s_waitcnt lgkmcnt(4)
	v_mfma_f32_32x32x16_bf16 v[66:81], v[136:139], v[152:155], v[66:81]
	ds_read_b64_tr_b16 v[148:149], v212 offset:18944
	ds_read_b64_tr_b16 v[150:151], v212 offset:23040
	ds_read_b64_tr_b16 v[152:153], v212 offset:27136
	ds_read_b64_tr_b16 v[154:155], v212 offset:31232
	s_waitcnt lgkmcnt(6)
	v_mfma_f32_32x32x16_bf16 v[50:65], v[132:135], v[140:143], v[50:65]
	s_waitcnt lgkmcnt(4)
	v_mfma_f32_32x32x16_bf16 v[50:65], v[136:139], v[144:147], v[50:65]
	ds_read_b64_tr_b16 v[140:141], v212 offset:19456
	ds_read_b64_tr_b16 v[142:143], v212 offset:23552
	ds_read_b64_tr_b16 v[144:145], v212 offset:27648
	ds_read_b64_tr_b16 v[146:147], v212 offset:31744
	s_waitcnt lgkmcnt(6)
	v_mfma_f32_32x32x16_bf16 v[34:49], v[132:135], v[148:151], v[34:49]
	s_waitcnt lgkmcnt(4)
	v_mfma_f32_32x32x16_bf16 v[34:49], v[136:139], v[152:155], v[34:49]
	ds_read_b64_tr_b16 v[148:149], v212 offset:19968
	ds_read_b64_tr_b16 v[150:151], v212 offset:24064
	ds_read_b64_tr_b16 v[152:153], v212 offset:28160
	ds_read_b64_tr_b16 v[154:155], v212 offset:32256
	s_waitcnt lgkmcnt(6)
	v_mfma_f32_32x32x16_bf16 v[18:33], v[132:135], v[140:143], v[18:33]
	s_waitcnt lgkmcnt(4)
	v_mfma_f32_32x32x16_bf16 v[18:33], v[136:139], v[144:147], v[18:33]
	s_waitcnt lgkmcnt(2)
	v_mfma_f32_32x32x16_bf16 v[2:17], v[132:135], v[148:151], v[2:17]
	s_waitcnt lgkmcnt(0)
	v_mfma_f32_32x32x16_bf16 v[2:17], v[136:139], v[152:155], v[2:17]
	s_setprio 0
	s_andn2_b32 s100, s100, 0x100
	s_bitcmp1_b32 s100, 9
	s_cbranch_scc1 .LBB0_113

; #define LAS __attribute__((address_space(3)))
; DI void attn_stage(const bf16_t* kbase, const bf16_t* vbase, unsigned koff, unsigned voff, LAS unsigned char* ldsbuf, int wid) {
; #pragma unroll
;     for (int i = 0; i < 2; ++i) {
;         const char* src = (const char*)kbase + (size_t)(i * 128) * 2;
;         __builtin_amdgcn_global_load_lds((const unsigned*)(src + koff), (LAS unsigned*)(ldsbuf + (wid + 8 * i) * 1024), 16, 0, 0);
;     }
; #pragma unroll
;     for (int i = 0; i < 2; ++i) {
;         const char* src = (const char*)vbase + (size_t)(16 * i * 2048) * 2;
;         __builtin_amdgcn_global_load_lds((const unsigned*)(src + voff), (LAS unsigned*)(ldsbuf + 16384 + (wid + 8 * i) * 1024), 16, 0, 0);
;     }
; }
; DI void phase_attn(int wid0, const Params& p, int L, unsigned char* lds, bool dry) {
;     ...
;             asm volatile("s_waitcnt vmcnt(0) lgkmcnt(0)" ::: "memory"); __builtin_amdgcn_s_barrier(); asm volatile("" ::: "memory");
;             if (t + 1 < ntiles) attn_stage(kh_ + (size_t)(b * 4096 + 32 * t) * 2048, vh_ + (size_t)(b * 4096 + 32 * t) * 2048, koff, voff, ldsl + 65536 + ((t + 1) & 1) * 32768, wid);
;             const int kpos0 = (t == 0) ? 0 : 16 + 32 * (t - 1);
.Lattn_top3:
	s_waitcnt vmcnt(0) lgkmcnt(0)
	s_barrier
	s_add_i32 s67, s69, 1
	s_cmp_ge_i32 s67, s6
	s_cbranch_scc1 .Lattn_nodma3
	s_add_i32 m0, s4, 0x0
	s_nop 0
	global_load_lds_dwordx4 v131, s[88:89]
	s_add_i32 m0, s4, 0x2000
	s_nop 0
	global_load_lds_dwordx4 v131, s[90:91]
	s_add_i32 m0, s96, 0x0
	s_add_u32 s88, s88, 0x20000
	global_load_lds_dwordx4 v208, s[92:93]
	s_addc_u32 s89, s89, 0
	s_add_i32 m0, s96, 0x2000
	s_add_u32 s92, s92, 0x20000
	global_load_lds_dwordx4 v208, s[94:95]
	s_addc_u32 s93, s93, 0
	s_add_u32 s94, s94, 0x20000
	s_addc_u32 s95, s95, 0
	s_add_u32 s90, s90, 0x20000
	s_addc_u32 s91, s91, 0

; DI void phase_attn(int wid0, const Params& p, int L, unsigned char* lds, bool dry) {
;     ...
;                 float pmax = p0[0];
; #pragma unroll
;                 for (int r = 1; r < 16; ++r) pmax = fmaxf(pmax, p0[r]);
;                 { auto rr = __builtin_amdgcn_permlane32_swap(__float_as_uint(pmax), __float_as_uint(pmax), false, false); pmax = fmaxf(__uint_as_float(rr[0]), __uint_as_float(rr[1])); }
;                 float mn, alpha;
;                 if (__all(pmax - m_reg <= ATT_THR2)) { mn = m_reg; alpha = 1.f; }
;                 else { mn = fmaxf(m_reg, pmax); alpha = __builtin_amdgcn_exp2f(m_reg - mn); m_reg = mn; }
;                 float ps = 0.f;
; #pragma unroll
;                 for (int r = 0; r < 16; ++r) { p0[r] = __builtin_amdgcn_exp2f(p0[r] - mn); ps += p0[r]; }
;                 { auto rr = __builtin_amdgcn_permlane32_swap(__float_as_uint(ps), __float_as_uint(ps), false, false); ps = __uint_as_float(rr[0]) + __uint_as_float(rr[1]); }
;                 l_reg = l_reg * alpha + ps;
;                 __builtin_amdgcn_sched_barrier(0);
;                 bf16x8 pa0, pa1;
;     ...
;                 PK4(p0, 0, pa0); PK4(p0, 8, pa1);
;     ...
;                 __builtin_amdgcn_sched_barrier(0);
;                 if (__any(alpha < 1.f)) {
;                     if (hi == 0) al_l[r32] = alpha;
;                     asm volatile("s_waitcnt lgkmcnt(0)" ::: "memory");
;                     float ar[16];
; #pragma unroll
;                     for (int r = 0; r < 16; ++r) ar[r] = al_l[crow(r, hi)];
; #pragma unroll
;                     for (int d = 0; d < 8; ++d)
; #pragma unroll
;                         for (int r = 0; r < 16; ++r) o[d][r] *= ar[r];
;                 }
;                 __builtin_amdgcn_sched_barrier(0);
;                 LAS unsigned char* vbp = ldsl + 65536 + (t & 1) * 32768 + 16384 + v_rd_base(lane);
;                 __builtin_amdgcn_s_setprio(1);
;     ...
;                 {
;                     s16x4 a0, a1, a2, a3, b0_, b1_, b2_, b3_;
;                     PV_RD(0, a0, a1, a2, a3); SB();
;                     PV_RD(1, b0_, b1_, b2_, b3_); SB(); PV_MM(0, a0, a1, a2, a3); SB();
;                     PV_RD(2, a0, a1, a2, a3); SB(); PV_MM(1, b0_, b1_, b2_, b3_); SB();
;                     PV_RD(3, b0_, b1_, b2_, b3_); SB(); PV_MM(2, a0, a1, a2, a3); SB();
;                     PV_RD(4, a0, a1, a2, a3); SB(); PV_MM(3, b0_, b1_, b2_, b3_); SB();
.Lattn_region3:
	ds_read_b64_tr_b16 v[216:217], v212 offset:32768
	ds_read_b64_tr_b16 v[218:219], v212 offset:36864
	ds_read_b64_tr_b16 v[220:221], v212 offset:40960
	ds_read_b64_tr_b16 v[222:223], v212 offset:45056
	ds_read_b64_tr_b16 v[236:237], v212 offset:33280
	ds_read_b64_tr_b16 v[238:239], v212 offset:37376
	ds_read_b64_tr_b16 v[240:241], v212 offset:41472
	ds_read_b64_tr_b16 v[242:243], v212 offset:45568
	s_waitcnt lgkmcnt(6)
	v_mfma_f32_32x32x16_bf16 v[114:129], v[156:159], v[216:219], v[114:129]
	s_waitcnt lgkmcnt(4)
	v_mfma_f32_32x32x16_bf16 v[114:129], v[160:163], v[220:223], v[114:129]
	v_max3_f32 v226, v140, v141, v142
	v_max3_f32 v226, v226, v143, v144
	v_max3_f32 v226, v226, v145, v146
	v_max3_f32 v226, v226, v147, v148
	v_max3_f32 v226, v226, v149, v150
	v_max3_f32 v226, v226, v151, v152
	v_max3_f32 v226, v226, v153, v154
	ds_read_b64_tr_b16 v[216:217], v212 offset:33792
	ds_read_b64_tr_b16 v[218:219], v212 offset:37888
	ds_read_b64_tr_b16 v[220:221], v212 offset:41984
	ds_read_b64_tr_b16 v[222:223], v212 offset:46080
	s_waitcnt lgkmcnt(6)
	v_mfma_f32_32x32x16_bf16 v[98:113], v[156:159], v[236:239], v[98:113]
	v_max_f32_e32 v226, v226, v155
	v_mov_b32_e32 v227, v226
	s_nop 1
	v_permlane32_swap_b32_e32 v226, v227
	v_max_f32_e32 v226, v226, v227
	v_fma_f32 v226, v226, s82, v231
	v_sub_f32_e32 v227, v226, v213
	s_mov_b32 s48, 0x4138aa3b
	s_waitcnt lgkmcnt(4)
	v_mfma_f32_32x32x16_bf16 v[98:113], v[160:163], v[240:243], v[98:113]
	v_cmp_ge_f32_e32 vcc, s48, v227
	s_cmp_eq_u64 vcc, exec
	v_max_f32_e32 v226, v213, v226
	s_cselect_b64 vcc, -1, 0
	v_sub_f32_e32 v227, v213, v226
	v_cndmask_b32_e32 v213, v226, v213, vcc
	v_sub_f32_e32 v230, v231, v213
	v_fma_f32 v140, v140, s82, v230
	ds_read_b64_tr_b16 v[236:237], v212 offset:34304
	ds_read_b64_tr_b16 v[238:239], v212 offset:38400
	ds_read_b64_tr_b16 v[240:241], v212 offset:42496
	ds_read_b64_tr_b16 v[242:243], v212 offset:46592
	s_waitcnt lgkmcnt(6)
	v_mfma_f32_32x32x16_bf16 v[82:97], v[156:159], v[216:219], v[82:97]
	v_exp_f32_e32 v140, v140
	v_fma_f32 v141, v141, s82, v230
	v_exp_f32_e32 v141, v141
	v_fma_f32 v142, v142, s82, v230
	v_exp_f32_e32 v142, v142
	s_waitcnt lgkmcnt(4)
	v_mfma_f32_32x32x16_bf16 v[82:97], v[160:163], v[220:223], v[82:97]
	v_add_f32_e32 v226, v140, v141
	v_fma_f32 v143, v143, s82, v230
	v_exp_f32_e32 v143, v143
	v_add_f32_e32 v226, v226, v142
	v_fma_f32 v144, v144, s82, v230
	v_exp_f32_e32 v144, v144
	ds_read_b64_tr_b16 v[216:217], v212 offset:34816
	ds_read_b64_tr_b16 v[218:219], v212 offset:38912
	ds_read_b64_tr_b16 v[220:221], v212 offset:43008
	ds_read_b64_tr_b16 v[222:223], v212 offset:47104
	s_waitcnt lgkmcnt(6)
	v_mfma_f32_32x32x16_bf16 v[66:81], v[156:159], v[236:239], v[66:81]
	v_add_f32_e32 v226, v226, v143
	v_fma_f32 v145, v145, s82, v230
	v_exp_f32_e32 v145, v145
	v_add_f32_e32 v226, v226, v144
	v_fma_f32 v146, v146, s82, v230
	v_exp_f32_e32 v146, v146
	s_waitcnt lgkmcnt(4)
	v_mfma_f32_32x32x16_bf16 v[66:81], v[160:163], v[240:243], v[66:81]
	v_add_f32_e32 v226, v226, v145
	v_fma_f32 v147, v147, s82, v230
	v_exp_f32_e32 v147, v147
	v_add_f32_e32 v226, v226, v146
	v_fma_f32 v148, v148, s82, v230
	v_exp_f32_e32 v148, v148
	ds_read_b64_tr_b16 v[236:237], v212 offset:35328
	ds_read_b64_tr_b16 v[238:239], v212 offset:39424
	ds_read_b64_tr_b16 v[240:241], v212 offset:43520
	ds_read_b64_tr_b16 v[242:243], v212 offset:47616
	s_waitcnt lgkmcnt(6)
	v_mfma_f32_32x32x16_bf16 v[50:65], v[156:159], v[216:219], v[50:65]
	v_add_f32_e32 v226, v226, v147
	v_fma_f32 v149, v149, s82, v230
	v_exp_f32_e32 v149, v149
	v_add_f32_e32 v226, v226, v148
	v_fma_f32 v150, v150, s82, v230
	v_exp_f32_e32 v150, v150
	s_waitcnt lgkmcnt(4)
	v_mfma_f32_32x32x16_bf16 v[50:65], v[160:163], v[220:223], v[50:65]
	v_add_f32_e32 v226, v226, v149
	v_fma_f32 v151, v151, s82, v230
	v_exp_f32_e32 v151, v151
	v_add_f32_e32 v226, v226, v150
	v_fma_f32 v152, v152, s82, v230
	ds_read_b64_tr_b16 v[216:217], v212 offset:35840
	ds_read_b64_tr_b16 v[218:219], v212 offset:39936
	ds_read_b64_tr_b16 v[220:221], v212 offset:44032
	ds_read_b64_tr_b16 v[222:223], v212 offset:48128
	s_waitcnt lgkmcnt(6)
	v_mfma_f32_32x32x16_bf16 v[34:49], v[156:159], v[236:239], v[34:49]
	v_exp_f32_e32 v152, v152
	v_add_f32_e32 v226, v226, v151
	v_fma_f32 v153, v153, s82, v230
	v_exp_f32_e32 v153, v153
	s_waitcnt lgkmcnt(4)
	v_mfma_f32_32x32x16_bf16 v[34:49], v[160:163], v[240:243], v[34:49]
	v_add_f32_e32 v226, v226, v152
	v_fma_f32 v154, v154, s82, v230
	v_exp_f32_e32 v154, v154
	v_add_f32_e32 v226, v226, v153
	v_fma_f32 v155, v155, s82, v230
	ds_read_b64_tr_b16 v[236:237], v212 offset:36352
	ds_read_b64_tr_b16 v[238:239], v212 offset:40448
	ds_read_b64_tr_b16 v[240:241], v212 offset:44544
	ds_read_b64_tr_b16 v[242:243], v212 offset:48640
	s_waitcnt lgkmcnt(6)
	v_mfma_f32_32x32x16_bf16 v[18:33], v[156:159], v[216:219], v[18:33]
	v_exp_f32_e32 v155, v155
	v_add_f32_e32 v226, v226, v154
	v_exp_f32_e32 v227, v227
	v_add_f32_e32 v228, v226, v155
	s_waitcnt lgkmcnt(4)
	v_mfma_f32_32x32x16_bf16 v[18:33], v[160:163], v[220:223], v[18:33]
	v_cndmask_b32_e64 v227, v227, 1.0, vcc
	v_mov_b32_e32 v229, v228
	v_cvt_pk_bf16_f32 v132, v140, v141
	v_cvt_pk_bf16_f32 v133, v142, v143
	v_cvt_pk_bf16_f32 v134, v144, v145
	v_cvt_pk_bf16_f32 v135, v146, v147
	s_waitcnt lgkmcnt(2)
	v_mfma_f32_32x32x16_bf16 v[2:17], v[156:159], v[236:239], v[2:17]
	v_cvt_pk_bf16_f32 v136, v148, v149
	v_cvt_pk_bf16_f32 v137, v150, v151
	v_cvt_pk_bf16_f32 v138, v152, v153
	v_cvt_pk_bf16_f32 v139, v154, v155
	v_permlane32_swap_b32_e32 v228, v229
	v_permlane32_swap_b32_e32 v132, v134
	s_waitcnt lgkmcnt(0)
	v_mfma_f32_32x32x16_bf16 v[2:17], v[160:163], v[240:243], v[2:17]
	v_permlane32_swap_b32_e32 v133, v135
	v_permlane32_swap_b32_e32 v136, v138
	v_permlane32_swap_b32_e32 v137, v139
	v_add_f32_e32 v228, v228, v229
	v_fma_f32 v130, v130, v227, v228
	v_cmp_gt_f32_e32 vcc, 1.0, v227
	s_cbranch_vccz .Lattn_norescale3
; DI int crow(int r, int hi) { return (r & 3) + 8 * (r >> 2) + 4 * hi; }
; DI void phase_attn(int wid0, const Params& p, int L, unsigned char* lds, bool dry) {
;     ...
;                 if (__any(alpha < 1.f)) {
;                     if (hi == 0) al_l[r32] = alpha;
;                     asm volatile("s_waitcnt lgkmcnt(0)" ::: "memory");
;                     float ar[16];
; #pragma unroll
;                     for (int r = 0; r < 16; ++r) ar[r] = al_l[crow(r, hi)];
; #pragma unroll
;                     for (int d = 0; d < 8; ++d)
; #pragma unroll
;                         for (int r = 0; r < 16; ++r) o[d][r] *= ar[r];
;                 }
	s_and_saveexec_b64 s[80:81], s[8:9]
	ds_write_b32 v196, v227 offset:128
	s_or_b64 exec, exec, s[80:81]
	s_waitcnt lgkmcnt(0)
	ds_read_b128 v[152:155], v214 offset:224
	ds_read_b128 v[148:151], v214 offset:192
	ds_read_b128 v[144:147], v214 offset:160
	ds_read_b128 v[140:143], v214 offset:128
	s_waitcnt lgkmcnt(0)
	v_pk_mul_f32 v[126:127], v[126:127], v[152:153]
	v_pk_mul_f32 v[122:123], v[122:123], v[148:149]
	v_pk_mul_f32 v[118:119], v[118:119], v[144:145]
	v_pk_mul_f32 v[128:129], v[128:129], v[154:155]
	v_pk_mul_f32 v[124:125], v[124:125], v[150:151]
	v_pk_mul_f32 v[120:121], v[120:121], v[146:147]
	v_pk_mul_f32 v[116:117], v[116:117], v[142:143]
	v_pk_mul_f32 v[114:115], v[114:115], v[140:141]
	v_pk_mul_f32 v[110:111], v[110:111], v[152:153]
	v_pk_mul_f32 v[106:107], v[106:107], v[148:149]
	v_pk_mul_f32 v[102:103], v[102:103], v[144:145]
	v_pk_mul_f32 v[112:113], v[112:113], v[154:155]
	v_pk_mul_f32 v[108:109], v[108:109], v[150:151]
	v_pk_mul_f32 v[104:105], v[104:105], v[146:147]
	v_pk_mul_f32 v[100:101], v[100:101], v[142:143]
	v_pk_mul_f32 v[98:99], v[98:99], v[140:141]
	v_pk_mul_f32 v[94:95], v[94:95], v[152:153]
	v_pk_mul_f32 v[90:91], v[90:91], v[148:149]
	v_pk_mul_f32 v[86:87], v[86:87], v[144:145]
	v_pk_mul_f32 v[96:97], v[96:97], v[154:155]
	v_pk_mul_f32 v[92:93], v[92:93], v[150:151]
	v_pk_mul_f32 v[88:89], v[88:89], v[146:147]
	v_pk_mul_f32 v[84:85], v[84:85], v[142:143]
	v_pk_mul_f32 v[82:83], v[82:83], v[140:141]
	v_pk_mul_f32 v[78:79], v[78:79], v[152:153]
	v_pk_mul_f32 v[74:75], v[74:75], v[148:149]
	v_pk_mul_f32 v[70:71], v[70:71], v[144:145]
	v_pk_mul_f32 v[80:81], v[80:81], v[154:155]
	v_pk_mul_f32 v[76:77], v[76:77], v[150:151]
	v_pk_mul_f32 v[72:73], v[72:73], v[146:147]
	v_pk_mul_f32 v[68:69], v[68:69], v[142:143]
	v_pk_mul_f32 v[66:67], v[66:67], v[140:141]
	v_pk_mul_f32 v[62:63], v[62:63], v[152:153]
	v_pk_mul_f32 v[58:59], v[58:59], v[148:149]
	v_pk_mul_f32 v[54:55], v[54:55], v[144:145]
	v_pk_mul_f32 v[64:65], v[64:65], v[154:155]
	v_pk_mul_f32 v[60:61], v[60:61], v[150:151]
	v_pk_mul_f32 v[56:57], v[56:57], v[146:147]
	v_pk_mul_f32 v[52:53], v[52:53], v[142:143]
	v_pk_mul_f32 v[50:51], v[50:51], v[140:141]
	v_pk_mul_f32 v[46:47], v[46:47], v[152:153]
	v_pk_mul_f32 v[42:43], v[42:43], v[148:149]
	v_pk_mul_f32 v[38:39], v[38:39], v[144:145]
	v_pk_mul_f32 v[48:49], v[48:49], v[154:155]
	v_pk_mul_f32 v[44:45], v[44:45], v[150:151]
	v_pk_mul_f32 v[40:41], v[40:41], v[146:147]
	v_pk_mul_f32 v[36:37], v[36:37], v[142:143]
	v_pk_mul_f32 v[34:35], v[34:35], v[140:141]
	v_pk_mul_f32 v[30:31], v[30:31], v[152:153]
	v_pk_mul_f32 v[26:27], v[26:27], v[148:149]
	v_pk_mul_f32 v[22:23], v[22:23], v[144:145]
	v_pk_mul_f32 v[32:33], v[32:33], v[154:155]
	v_pk_mul_f32 v[28:29], v[28:29], v[150:151]
	v_pk_mul_f32 v[24:25], v[24:25], v[146:147]
	v_pk_mul_f32 v[20:21], v[20:21], v[142:143]
	v_pk_mul_f32 v[18:19], v[18:19], v[140:141]
	v_pk_mul_f32 v[14:15], v[14:15], v[152:153]
	v_pk_mul_f32 v[10:11], v[10:11], v[148:149]
	v_pk_mul_f32 v[6:7], v[6:7], v[144:145]
	v_pk_mul_f32 v[16:17], v[16:17], v[154:155]
	v_pk_mul_f32 v[12:13], v[12:13], v[150:151]
	v_pk_mul_f32 v[8:9], v[8:9], v[146:147]
	v_pk_mul_f32 v[4:5], v[4:5], v[142:143]
	v_pk_mul_f32 v[2:3], v[2:3], v[140:141]

; #define LAS __attribute__((address_space(3)))
; DI int v_rd_base(int lane) { return ((lane & 3) << 3) | (((lane >> 2) & 3) << 6) | (((lane >> 4) & 1) << 5) | (((lane >> 5) & 1) << 8); }
; #define PV_RD(D0, L0, H0, L1, H1) L0 = TRB(v_rd_off(D0, 0, 0)); H0 = TRB(v_rd_off(D0, 0, 1)); L1 = TRB(v_rd_off(D0, 1, 0)); H1 = TRB(v_rd_off(D0, 1, 1))
; #define PV_MM(D0, L0, H0, L1, H1) o[D0] = MFMA32(pa0, PK8(L0, H0), o[D0]); o[D0] = MFMA32(pa1, PK8(L1, H1), o[D0])
; #define SB() __builtin_amdgcn_sched_barrier(0)
; DI void phase_attn(int wid0, const Params& p, int L, unsigned char* lds, bool dry) {
;     ...
;         for (int t = 0; t < ntiles; ++t) {
;     ...
;                 LAS unsigned char* vbp = ldsl + 65536 + (t & 1) * 32768 + 16384 + v_rd_base(lane);
;                 __builtin_amdgcn_s_setprio(1);
;     ...
;                 {
;                     s16x4 a0, a1, a2, a3, b0_, b1_, b2_, b3_;
;                     PV_RD(0, a0, a1, a2, a3); SB();
;                     PV_RD(1, b0_, b1_, b2_, b3_); SB(); PV_MM(0, a0, a1, a2, a3); SB();
;                     PV_RD(2, a0, a1, a2, a3); SB(); PV_MM(1, b0_, b1_, b2_, b3_); SB();
;                     PV_RD(3, b0_, b1_, b2_, b3_); SB(); PV_MM(2, a0, a1, a2, a3); SB();
;                     PV_RD(4, a0, a1, a2, a3); SB(); PV_MM(3, b0_, b1_, b2_, b3_); SB();
;                     PV_RD(5, b0_, b1_, b2_, b3_); SB(); PV_MM(4, a0, a1, a2, a3); SB();
;                     PV_RD(6, a0, a1, a2, a3); SB(); PV_MM(5, b0_, b1_, b2_, b3_); SB();
;                     PV_RD(7, b0_, b1_, b2_, b3_); SB(); PV_MM(6, a0, a1, a2, a3); SB();
;                     PV_MM(7, b0_, b1_, b2_, b3_); SB();
;                 }
;     ...
;                 __builtin_amdgcn_s_setprio(0);
.Lattn_pvplain2:
	s_setprio 1
	ds_read_b64_tr_b16 v[140:141], v212 offset:32768
	ds_read_b64_tr_b16 v[142:143], v212 offset:36864
	ds_read_b64_tr_b16 v[144:145], v212 offset:40960
	ds_read_b64_tr_b16 v[146:147], v212 offset:45056
	ds_read_b64_tr_b16 v[148:149], v212 offset:33280
	ds_read_b64_tr_b16 v[150:151], v212 offset:37376
	ds_read_b64_tr_b16 v[152:153], v212 offset:41472
	ds_read_b64_tr_b16 v[154:155], v212 offset:45568
	s_waitcnt lgkmcnt(6)
	v_mfma_f32_32x32x16_bf16 v[114:129], v[156:159], v[140:143], v[114:129]
	s_waitcnt lgkmcnt(4)
	v_mfma_f32_32x32x16_bf16 v[114:129], v[160:163], v[144:147], v[114:129]
	ds_read_b64_tr_b16 v[140:141], v212 offset:33792
	ds_read_b64_tr_b16 v[142:143], v212 offset:37888
	ds_read_b64_tr_b16 v[144:145], v212 offset:41984
	ds_read_b64_tr_b16 v[146:147], v212 offset:46080
	s_waitcnt lgkmcnt(6)
	v_mfma_f32_32x32x16_bf16 v[98:113], v[156:159], v[148:151], v[98:113]
	s_waitcnt lgkmcnt(4)
	v_mfma_f32_32x32x16_bf16 v[98:113], v[160:163], v[152:155], v[98:113]
	ds_read_b64_tr_b16 v[148:149], v212 offset:34304
	ds_read_b64_tr_b16 v[150:151], v212 offset:38400
	ds_read_b64_tr_b16 v[152:153], v212 offset:42496
	ds_read_b64_tr_b16 v[154:155], v212 offset:46592
	s_waitcnt lgkmcnt(6)
	v_mfma_f32_32x32x16_bf16 v[82:97], v[156:159], v[140:143], v[82:97]
	s_waitcnt lgkmcnt(4)
	v_mfma_f32_32x32x16_bf16 v[82:97], v[160:163], v[144:147], v[82:97]
	ds_read_b64_tr_b16 v[140:141], v212 offset:34816
	ds_read_b64_tr_b16 v[142:143], v212 offset:38912
	ds_read_b64_tr_b16 v[144:145], v212 offset:43008
	ds_read_b64_tr_b16 v[146:147], v212 offset:47104
	s_waitcnt lgkmcnt(6)
	v_mfma_f32_32x32x16_bf16 v[66:81], v[156:159], v[148:151], v[66:81]
	s_waitcnt lgkmcnt(4)
	v_mfma_f32_32x32x16_bf16 v[66:81], v[160:163], v[152:155], v[66:81]
	ds_read_b64_tr_b16 v[148:149], v212 offset:35328
	ds_read_b64_tr_b16 v[150:151], v212 offset:39424
	ds_read_b64_tr_b16 v[152:153], v212 offset:43520
	ds_read_b64_tr_b16 v[154:155], v212 offset:47616
	s_waitcnt lgkmcnt(6)
	v_mfma_f32_32x32x16_bf16 v[50:65], v[156:159], v[140:143], v[50:65]
	s_waitcnt lgkmcnt(4)
	v_mfma_f32_32x32x16_bf16 v[50:65], v[160:163], v[144:147], v[50:65]
	ds_read_b64_tr_b16 v[140:141], v212 offset:35840
	ds_read_b64_tr_b16 v[142:143], v212 offset:39936
	ds_read_b64_tr_b16 v[144:145], v212 offset:44032
	ds_read_b64_tr_b16 v[146:147], v212 offset:48128
	s_waitcnt lgkmcnt(6)
	v_mfma_f32_32x32x16_bf16 v[34:49], v[156:159], v[148:151], v[34:49]
	s_waitcnt lgkmcnt(4)
	v_mfma_f32_32x32x16_bf16 v[34:49], v[160:163], v[152:155], v[34:49]
	ds_read_b64_tr_b16 v[148:149], v212 offset:36352
	ds_read_b64_tr_b16 v[150:151], v212 offset:40448
	ds_read_b64_tr_b16 v[152:153], v212 offset:44544
	ds_read_b64_tr_b16 v[154:155], v212 offset:48640
	s_waitcnt lgkmcnt(6)
	v_mfma_f32_32x32x16_bf16 v[18:33], v[156:159], v[140:143], v[18:33]
	s_waitcnt lgkmcnt(4)
	v_mfma_f32_32x32x16_bf16 v[18:33], v[160:163], v[144:147], v[18:33]
	s_waitcnt lgkmcnt(2)
	v_mfma_f32_32x32x16_bf16 v[2:17], v[156:159], v[148:151], v[2:17]
	s_waitcnt lgkmcnt(0)
	v_mfma_f32_32x32x16_bf16 v[2:17], v[160:163], v[152:155], v[2:17]
	s_setprio 0
	s_andn2_b32 s100, s100, 0x100
	s_bitcmp1_b32 s100, 9
	s_cbranch_scc1 .LBB0_113
.Lattn_latch3:
	s_sub_i32 s39, s39, 32
	s_add_i32 s7, s7, 32
	s_cmp_eq_u32 s6, s67
	s_cbranch_scc1 .Lattn_exit3
	s_mov_b32 s69, s67
	s_branch .LBB0_99

; __global__ void __launch_bounds__(512) mega(Params p_arg) {
;     extern __shared__ __attribute__((aligned(16))) unsigned char lds[];
	.amdhsa_kernel _Z4mega6Params
		.amdhsa_group_segment_fixed_size 0
		.amdhsa_private_segment_fixed_size 0
		.amdhsa_kernarg_size 392
		.amdhsa_user_sgpr_count 2
		.amdhsa_user_sgpr_dispatch_ptr 0
		.amdhsa_user_sgpr_queue_ptr 0
		.amdhsa_user_sgpr_kernarg_segment_ptr 1
		.amdhsa_user_sgpr_dispatch_id 0
		.amdhsa_user_sgpr_kernarg_preload_length 0
		.amdhsa_user_sgpr_kernarg_preload_offset 0
		.amdhsa_user_sgpr_private_segment_size 0
		.amdhsa_uses_dynamic_stack 0
		.amdhsa_enable_private_segment 0
		.amdhsa_system_sgpr_workgroup_id_x 1
		.amdhsa_system_sgpr_workgroup_id_y 0
		.amdhsa_system_sgpr_workgroup_id_z 0
		.amdhsa_system_sgpr_workgroup_info 0
		.amdhsa_system_vgpr_workitem_id 2
		.amdhsa_next_free_vgpr 256
		.amdhsa_next_free_sgpr 102
		.amdhsa_accum_offset 256
		.amdhsa_reserve_vcc 1
		.amdhsa_float_round_mode_32 0
		.amdhsa_float_round_mode_16_64 0
		.amdhsa_float_denorm_mode_32 3
		.amdhsa_float_denorm_mode_16_64 3
		.amdhsa_dx10_clamp 1
		.amdhsa_ieee_mode 1
		.amdhsa_fp16_overflow 0
		.amdhsa_tg_split 0
		.amdhsa_exception_fp_ieee_invalid_op 0
		.amdhsa_exception_fp_denorm_src 0
		.amdhsa_exception_fp_ieee_div_zero 0
		.amdhsa_exception_fp_ieee_overflow 0
		.amdhsa_exception_fp_ieee_underflow 0
		.amdhsa_exception_fp_ieee_inexact 0
		.amdhsa_exception_int_div_zero 0
	.end_amdhsa_kernel

; __global__ void __launch_bounds__(512) mega(Params p_arg) {
amdhsa.kernels:
  - .agpr_count:     0
    .args:
      - .offset:         0
        .size:           136
        .value_kind:     by_value
      - .offset:         136
        .size:           4
        .value_kind:     hidden_block_count_x
      - .offset:         140
        .size:           4
        .value_kind:     hidden_block_count_y
      - .offset:         144
        .size:           4
        .value_kind:     hidden_block_count_z
      - .offset:         148
        .size:           2
        .value_kind:     hidden_group_size_x
      - .offset:         150
        .size:           2
        .value_kind:     hidden_group_size_y
      - .offset:         152
        .size:           2
        .value_kind:     hidden_group_size_z
      - .offset:         154
        .size:           2
        .value_kind:     hidden_remainder_x
      - .offset:         156
        .size:           2
        .value_kind:     hidden_remainder_y
      - .offset:         158
        .size:           2
        .value_kind:     hidden_remainder_z
      - .offset:         176
        .size:           8
        .value_kind:     hidden_global_offset_x
      - .offset:         184
        .size:           8
        .value_kind:     hidden_global_offset_y
      - .offset:         192
        .size:           8
        .value_kind:     hidden_global_offset_z
      - .offset:         200
        .size:           2
        .value_kind:     hidden_grid_dims
      - .offset:         224
        .size:           8
        .value_kind:     hidden_multigrid_sync_arg
      - .offset:         256
        .size:           4
        .value_kind:     hidden_dynamic_lds_size
    .group_segment_fixed_size: 0
    .kernarg_segment_align: 8
    .kernarg_segment_size: 392
    .language:       OpenCL C
    .language_version:
      - 2
      - 0
    .max_flat_workgroup_size: 512
    .name:           _Z4mega6Params
    .private_segment_fixed_size: 0
    .sgpr_count:     108
    .sgpr_spill_count: 207
    .symbol:         _Z4mega6Params.kd
    .uniform_work_group_size: 1
    .uses_dynamic_stack: false
    .vgpr_count:     256
    .vgpr_spill_count: 0
    .wavefront_size: 64
